# NA: v_perm V pack, out-of-place rotation, cvt_pk P pack (nop-preserving); fold items 3/5 between GEMM and non-GEMM workgroups
# speedup vs baseline: 1.0767x; 1.0011x over previous
; __device__ __forceinline__ void na2_task(const Params& p_, int l, int task, unsigned char* lds) {
;     ...
;     for (int i = 0; i < 8; ++i) { const int a = i / 2, ci = i % 2;
;         const size_t ktok = (size_t)b * SEQ + (row_start + a) * 64 + kst + 16 * ci + fr;
; #pragma unroll
;         for (int ks = 0; ks < 2; ++ks) kfr[i][ks] = *(const bf16x8v*)(Z + ktok * DIN + 3 * DG + h * 64 + 32 * ks + 8 * fq); }
;     asm volatile("" ::: "memory");
;     for (int i = tid; i < 930; i += NTHR) BI[i] = p.na_bias[(size_t)(l * 8 + hp * 2) * 465 + i];
;     { const int pair = lane & 31, chunk = (lane >> 5) + 2 * (w & 3);
;       unsigned* VTd = (unsigned*)(VT + (size_t)hh * 64 * 520);
;       u32x4 xs[8], ys[8];
; #pragma unroll
;       for (int a = 0; a < 8; ++a) { const size_t tok = (size_t)b * SEQ + (row_start + a) * 64 + 2 * pair;
;           const bf16* src = Z + tok * DIN + 4 * DG + h * 64 + chunk * 8; xs[a] = *(const u32x4*)src; ys[a] = *(const u32x4*)(src + DIN); }
.LBB0_385:
	v_bfe_u32 v172, v147, 2, 3
	v_bfe_u32 v249, v147, 6, 2
	v_lshl_or_b32 v172, v249, 3, v172
	v_lshl_or_b32 v88, v172, 1, s42
	v_or_b32_e32 v81, s24, v88
	v_mov_b64_e32 v[86:87], s[40:41]
	v_and_b32_e32 v173, 3, v147
	v_bfe_u32 v249, v147, 5, 1
	v_lshl_or_b32 v173, v249, 2, v173
	v_lshlrev_b32_e32 v173, 3, v173
	v_mad_u64_u32 v[94:95], s[40:41], v81, s75, v[86:87]
	v_mad_i32_i24 v95, s43, v195, v95
	v_mov_b32_e32 v89, s43
	v_lshl_add_u64 v[94:95], v[94:95], 0, v[76:77]
	v_lshlrev_b32_e32 v164, 1, v173
	v_mov_b32_e32 v165, v1
	v_lshl_add_u64 v[94:95], v[94:95], 0, v[164:165]
	v_lshl_add_u64 v[102:103], v[88:89], 0, s[44:45]
	v_add_co_u32_e32 v96, vcc, s74, v94
	v_mad_u64_u32 v[104:105], s[40:41], v102, s75, v[86:87]
	s_nop 0
	v_addc_co_u32_e32 v97, vcc, 0, v95, vcc
	v_mad_i32_i24 v105, v103, s75, v105
	v_add_co_u32_e32 v98, vcc, s7, v94
	v_lshl_add_u64 v[102:103], v[104:105], 0, v[76:77]
	s_nop 0
	v_addc_co_u32_e32 v99, vcc, 0, v95, vcc
	v_lshl_add_u64 v[102:103], v[102:103], 0, v[164:165]
	global_load_dwordx4 v[94:97], v[96:97], off
	s_nop 0
	global_load_dwordx4 v[98:101], v[98:99], off offset:1024
	v_add_co_u32_e32 v104, vcc, s74, v102
	v_lshl_add_u64 v[110:111], v[88:89], 0, s[46:47]
	s_nop 0
	v_addc_co_u32_e32 v105, vcc, 0, v103, vcc
	v_add_co_u32_e32 v106, vcc, s7, v102
	v_mad_u64_u32 v[112:113], s[40:41], v110, s75, v[86:87]
	s_nop 0
	v_addc_co_u32_e32 v107, vcc, 0, v103, vcc
	global_load_dwordx4 v[102:105], v[104:105], off
	s_nop 0
	global_load_dwordx4 v[106:109], v[106:107], off offset:1024
	v_mad_i32_i24 v113, v111, s75, v113
	v_lshl_add_u64 v[110:111], v[112:113], 0, v[76:77]
	v_lshl_add_u64 v[110:111], v[110:111], 0, v[164:165]
	v_lshl_add_u64 v[118:119], v[88:89], 0, s[48:49]
	v_add_co_u32_e32 v112, vcc, s74, v110
	v_mad_u64_u32 v[120:121], s[40:41], v118, s75, v[86:87]
	s_nop 0
	v_addc_co_u32_e32 v113, vcc, 0, v111, vcc
	v_mad_i32_i24 v121, v119, s75, v121
	v_add_co_u32_e32 v114, vcc, s7, v110
	v_lshl_add_u64 v[118:119], v[120:121], 0, v[76:77]
	s_nop 0
	v_addc_co_u32_e32 v115, vcc, 0, v111, vcc
	v_lshl_add_u64 v[118:119], v[118:119], 0, v[164:165]
	v_add_co_u32_e32 v120, vcc, s74, v118
	global_load_dwordx4 v[110:113], v[112:113], off
	s_nop 0
	global_load_dwordx4 v[114:117], v[114:115], off offset:1024
	v_addc_co_u32_e32 v121, vcc, 0, v119, vcc
	v_add_co_u32_e32 v122, vcc, s7, v118
	s_add_i32 s44, s24, 0x100
	s_nop 0
	v_addc_co_u32_e32 v123, vcc, 0, v119, vcc
	global_load_dwordx4 v[118:121], v[120:121], off
	s_nop 0
	global_load_dwordx4 v[122:125], v[122:123], off offset:1024
	s_mov_b32 s45, s25
	v_lshl_add_u64 v[126:127], v[88:89], 0, s[44:45]
	v_mad_u64_u32 v[128:129], s[40:41], v126, s75, v[86:87]
	v_mad_i32_i24 v129, v127, s75, v129
	v_lshl_add_u64 v[126:127], v[128:129], 0, v[76:77]
	s_add_i32 s42, s24, 0x140
	s_mov_b32 s43, s25
	v_lshl_add_u64 v[126:127], v[126:127], 0, v[164:165]
	v_lshl_add_u64 v[134:135], v[88:89], 0, s[42:43]
	v_add_co_u32_e32 v128, vcc, s74, v126
	v_mad_u64_u32 v[136:137], s[40:41], v134, s75, v[86:87]
	s_nop 0
	v_addc_co_u32_e32 v129, vcc, 0, v127, vcc
	v_mad_i32_i24 v137, v135, s75, v137
	v_add_co_u32_e32 v130, vcc, s7, v126
	v_lshl_add_u64 v[134:135], v[136:137], 0, v[76:77]
	s_nop 0
	v_addc_co_u32_e32 v131, vcc, 0, v127, vcc
	v_lshl_add_u64 v[134:135], v[134:135], 0, v[164:165]
	v_add_co_u32_e32 v136, vcc, s74, v134
	global_load_dwordx4 v[126:129], v[128:129], off
	s_nop 0
	global_load_dwordx4 v[130:133], v[130:131], off offset:1024
	v_addc_co_u32_e32 v137, vcc, 0, v135, vcc
	v_add_co_u32_e32 v138, vcc, s7, v134
	s_add_i32 s40, s24, 0x180
	s_nop 0
	v_addc_co_u32_e32 v139, vcc, 0, v135, vcc
	global_load_dwordx4 v[134:137], v[136:137], off
	s_nop 0
	global_load_dwordx4 v[138:141], v[138:139], off offset:1024
	s_mov_b32 s41, s25
	v_lshl_add_u64 v[142:143], v[88:89], 0, s[40:41]
	v_mad_u64_u32 v[144:145], s[46:47], v142, s75, v[86:87]
	v_mad_i32_i24 v145, v143, s75, v145
	v_lshl_add_u64 v[142:143], v[144:145], 0, v[76:77]
	s_addk_i32 s24, 0x1c0
	v_lshl_add_u64 v[142:143], v[142:143], 0, v[164:165]
	v_lshl_add_u64 v[88:89], v[88:89], 0, s[24:25]
	v_add_co_u32_e32 v144, vcc, s74, v142
	v_mad_u64_u32 v[166:167], s[46:47], v88, s75, v[86:87]
	s_nop 0
	v_addc_co_u32_e32 v145, vcc, 0, v143, vcc
	v_mad_i32_i24 v167, v89, s75, v167
	v_add_co_u32_e32 v160, vcc, s7, v142
	v_lshl_add_u64 v[88:89], v[166:167], 0, v[76:77]
	s_nop 0
	v_addc_co_u32_e32 v161, vcc, 0, v143, vcc
	v_lshl_add_u64 v[88:89], v[88:89], 0, v[164:165]
	v_add_co_u32_e32 v164, vcc, s74, v88
	global_load_dwordx4 v[142:145], v[144:145], off
	s_nop 0
	global_load_dwordx4 v[160:163], v[160:161], off offset:1024
	v_addc_co_u32_e32 v165, vcc, 0, v89, vcc
	v_add_co_u32_e32 v88, vcc, s7, v88
	s_mov_b32 s13, 0x10400
	s_nop 0
	v_addc_co_u32_e32 v89, vcc, 0, v89, vcc
	global_load_dwordx4 v[164:167], v[164:165], off
	s_nop 0
	global_load_dwordx4 v[168:171], v[88:89], off offset:1024
	v_add_u32_e32 v208, s44, v82
	v_mad_u64_u32 v[206:207], s[98:99], v208, s75, v[86:87]
	v_lshl_add_u64 v[206:207], v[206:207], 0, v[76:77]
	v_lshl_add_u64 v[206:207], v[206:207], 0, v[252:253]
	global_load_dwordx4 v[210:213], v[206:207], off offset:3072
	global_load_dwordx4 v[214:217], v[206:207], off offset:3136
	v_add_u32_e32 v208, s44, v84
	v_mad_u64_u32 v[206:207], s[98:99], v208, s75, v[86:87]
	v_lshl_add_u64 v[206:207], v[206:207], 0, v[76:77]
	v_lshl_add_u64 v[206:207], v[206:207], 0, v[252:253]
	global_load_dwordx4 v[218:221], v[206:207], off offset:3072
	global_load_dwordx4 v[222:225], v[206:207], off offset:3136
	v_add_u32_e32 v208, s42, v82
	v_mad_u64_u32 v[206:207], s[98:99], v208, s75, v[86:87]
	v_lshl_add_u64 v[206:207], v[206:207], 0, v[76:77]
	v_lshl_add_u64 v[206:207], v[206:207], 0, v[252:253]
	global_load_dwordx4 v[226:229], v[206:207], off offset:3072
	global_load_dwordx4 v[230:233], v[206:207], off offset:3136
	v_add_u32_e32 v208, s42, v84
	v_mad_u64_u32 v[206:207], s[98:99], v208, s75, v[86:87]
	v_lshl_add_u64 v[206:207], v[206:207], 0, v[76:77]
	v_lshl_add_u64 v[206:207], v[206:207], 0, v[252:253]
	global_load_dwordx4 v[234:237], v[206:207], off offset:3072
	s_waitcnt vmcnt(25)
; __device__ __forceinline__ void na2_task(const Params& p_, int l, int task, unsigned char* lds) {
;     ...
;     { const int pair = lane & 31, chunk = (lane >> 5) + 2 * (w & 3);
;       unsigned* VTd = (unsigned*)(VT + (size_t)hh * 64 * 520);
;       u32x4 xs[8], ys[8];
; #pragma unroll
;       for (int a = 0; a < 8; ++a) { const size_t tok = (size_t)b * SEQ + (row_start + a) * 64 + 2 * pair;
;           const bf16* src = Z + tok * DIN + 4 * DG + h * 64 + chunk * 8; xs[a] = *(const u32x4*)src; ys[a] = *(const u32x4*)(src + DIN); }
;       asm volatile("" ::: "memory");
; #pragma unroll
;       for (int a = 0; a < 8; ++a) { const unsigned xu[4] = {xs[a].x, xs[a].y, xs[a].z, xs[a].w}, yu[4] = {ys[a].x, ys[a].y, ys[a].z, ys[a].w};
; #pragma unroll
;           for (int i = 0; i < 4; ++i) { VTd[(chunk * 8 + 2 * i) * 260 + a * 32 + pair] = (xu[i] & 0xffffu) | (yu[i] << 16);
;               VTd[(chunk * 8 + 2 * i + 1) * 260 + a * 32 + pair] = (xu[i] >> 16) | (yu[i] & 0xffff0000u); } } }
	ds_bpermute_b32 v70, v251, v70
	ds_bpermute_b32 v71, v251, v71
	ds_bpermute_b32 v72, v251, v72
	ds_bpermute_b32 v73, v251, v73
	ds_bpermute_b32 v66, v251, v66
	ds_bpermute_b32 v67, v251, v67
	ds_bpermute_b32 v68, v251, v68
	ds_bpermute_b32 v69, v251, v69
	ds_bpermute_b32 v62, v251, v62
	ds_bpermute_b32 v63, v251, v63
	ds_bpermute_b32 v64, v251, v64
	ds_bpermute_b32 v65, v251, v65
	ds_bpermute_b32 v58, v251, v58
	ds_bpermute_b32 v59, v251, v59
	ds_bpermute_b32 v60, v251, v60
	ds_bpermute_b32 v61, v251, v61
	ds_bpermute_b32 v18, v251, v18
	ds_bpermute_b32 v19, v251, v19
	ds_bpermute_b32 v20, v251, v20
	ds_bpermute_b32 v21, v251, v21
	ds_bpermute_b32 v10, v251, v10
	ds_bpermute_b32 v11, v251, v11
	ds_bpermute_b32 v12, v251, v12
	ds_bpermute_b32 v13, v251, v13
	ds_bpermute_b32 v38, v251, v38
	ds_bpermute_b32 v39, v251, v39
	ds_bpermute_b32 v40, v251, v40
	ds_bpermute_b32 v41, v251, v41
	ds_bpermute_b32 v22, v251, v22
	ds_bpermute_b32 v23, v251, v23
	ds_bpermute_b32 v24, v251, v24
	ds_bpermute_b32 v25, v251, v25
	ds_bpermute_b32 v54, v251, v54
	ds_bpermute_b32 v55, v251, v55
	ds_bpermute_b32 v56, v251, v56
	ds_bpermute_b32 v57, v251, v57
	ds_bpermute_b32 v42, v251, v42
	ds_bpermute_b32 v43, v251, v43
	ds_bpermute_b32 v44, v251, v44
	ds_bpermute_b32 v45, v251, v45
	ds_bpermute_b32 v46, v251, v46
	ds_bpermute_b32 v47, v251, v47
	ds_bpermute_b32 v48, v251, v48
	ds_bpermute_b32 v49, v251, v49
	ds_bpermute_b32 v30, v251, v30
	ds_bpermute_b32 v31, v251, v31
	ds_bpermute_b32 v32, v251, v32
	ds_bpermute_b32 v33, v251, v33
	ds_bpermute_b32 v26, v251, v26
	ds_bpermute_b32 v27, v251, v27
	ds_bpermute_b32 v28, v251, v28
	ds_bpermute_b32 v29, v251, v29
	ds_bpermute_b32 v14, v251, v14
	ds_bpermute_b32 v15, v251, v15
	ds_bpermute_b32 v16, v251, v16
	ds_bpermute_b32 v17, v251, v17
	ds_bpermute_b32 v50, v251, v50
	ds_bpermute_b32 v51, v251, v51
	ds_bpermute_b32 v52, v251, v52
	ds_bpermute_b32 v53, v251, v53
	ds_bpermute_b32 v34, v251, v34
	ds_bpermute_b32 v35, v251, v35
	ds_bpermute_b32 v36, v251, v36
	ds_bpermute_b32 v37, v251, v37
	s_waitcnt vmcnt(7)
	v_and_b32_e32 v248, 1, v147
	v_cmp_eq_u32_e32 vcc, 1, v248
	v_and_b32_e32 v248, 2, v147
	v_cmp_eq_u32_e64 s[98:99], 2, v248
	s_nop 1
	v_cndmask_b32_e32 v246, v94, v95, vcc
	v_cndmask_b32_e32 v247, v95, v96, vcc
	v_cndmask_b32_e32 v248, v96, v97, vcc
	v_cndmask_b32_e32 v249, v97, v94, vcc
	v_cndmask_b32_e64 v94, v246, v248, s[98:99]
	v_cndmask_b32_e64 v95, v247, v249, s[98:99]
	v_cndmask_b32_e64 v96, v248, v246, s[98:99]
	v_cndmask_b32_e64 v97, v249, v247, s[98:99]
	v_cndmask_b32_e32 v246, v98, v99, vcc
	v_cndmask_b32_e32 v247, v99, v100, vcc
	v_cndmask_b32_e32 v248, v100, v101, vcc
	v_cndmask_b32_e32 v249, v101, v98, vcc
	v_cndmask_b32_e64 v98, v246, v248, s[98:99]
	v_cndmask_b32_e64 v99, v247, v249, s[98:99]
	v_cndmask_b32_e64 v100, v248, v246, s[98:99]
	v_cndmask_b32_e64 v101, v249, v247, s[98:99]
	v_cndmask_b32_e32 v246, v102, v103, vcc
	v_cndmask_b32_e32 v247, v103, v104, vcc
	v_cndmask_b32_e32 v248, v104, v105, vcc
	v_cndmask_b32_e32 v249, v105, v102, vcc
	v_cndmask_b32_e64 v102, v246, v248, s[98:99]
	v_cndmask_b32_e64 v103, v247, v249, s[98:99]
	v_cndmask_b32_e64 v104, v248, v246, s[98:99]
	v_cndmask_b32_e64 v105, v249, v247, s[98:99]
	v_cndmask_b32_e32 v246, v106, v107, vcc
	v_cndmask_b32_e32 v247, v107, v108, vcc
	v_cndmask_b32_e32 v248, v108, v109, vcc
	v_cndmask_b32_e32 v249, v109, v106, vcc
	v_cndmask_b32_e64 v106, v246, v248, s[98:99]
	v_cndmask_b32_e64 v107, v247, v249, s[98:99]
	v_cndmask_b32_e64 v108, v248, v246, s[98:99]
	v_cndmask_b32_e64 v109, v249, v247, s[98:99]
	v_cndmask_b32_e32 v246, v110, v111, vcc
	v_cndmask_b32_e32 v247, v111, v112, vcc
	v_cndmask_b32_e32 v248, v112, v113, vcc
	v_cndmask_b32_e32 v249, v113, v110, vcc
	v_cndmask_b32_e64 v110, v246, v248, s[98:99]
	v_cndmask_b32_e64 v111, v247, v249, s[98:99]
	v_cndmask_b32_e64 v112, v248, v246, s[98:99]
	v_cndmask_b32_e64 v113, v249, v247, s[98:99]
	v_cndmask_b32_e32 v246, v114, v115, vcc
	v_cndmask_b32_e32 v247, v115, v116, vcc
	v_cndmask_b32_e32 v248, v116, v117, vcc
	v_cndmask_b32_e32 v249, v117, v114, vcc
	v_cndmask_b32_e64 v114, v246, v248, s[98:99]
	v_cndmask_b32_e64 v115, v247, v249, s[98:99]
	v_cndmask_b32_e64 v116, v248, v246, s[98:99]
	v_cndmask_b32_e64 v117, v249, v247, s[98:99]
	v_cndmask_b32_e32 v246, v118, v119, vcc
	v_cndmask_b32_e32 v247, v119, v120, vcc
	v_cndmask_b32_e32 v248, v120, v121, vcc
	v_cndmask_b32_e32 v249, v121, v118, vcc
	v_cndmask_b32_e64 v118, v246, v248, s[98:99]
	v_cndmask_b32_e64 v119, v247, v249, s[98:99]
	v_cndmask_b32_e64 v120, v248, v246, s[98:99]
	v_cndmask_b32_e64 v121, v249, v247, s[98:99]
	v_cndmask_b32_e32 v246, v122, v123, vcc
	v_cndmask_b32_e32 v247, v123, v124, vcc
	v_cndmask_b32_e32 v248, v124, v125, vcc
	v_cndmask_b32_e32 v249, v125, v122, vcc
	v_cndmask_b32_e64 v122, v246, v248, s[98:99]
	v_cndmask_b32_e64 v123, v247, v249, s[98:99]
	v_cndmask_b32_e64 v124, v248, v246, s[98:99]
	v_cndmask_b32_e64 v125, v249, v247, s[98:99]
	v_cndmask_b32_e32 v246, v126, v127, vcc
	v_cndmask_b32_e32 v247, v127, v128, vcc
	v_cndmask_b32_e32 v248, v128, v129, vcc
	v_cndmask_b32_e32 v249, v129, v126, vcc
	v_cndmask_b32_e64 v126, v246, v248, s[98:99]
	v_cndmask_b32_e64 v127, v247, v249, s[98:99]
	v_cndmask_b32_e64 v128, v248, v246, s[98:99]
	v_cndmask_b32_e64 v129, v249, v247, s[98:99]
	v_cndmask_b32_e32 v246, v130, v131, vcc
	v_cndmask_b32_e32 v247, v131, v132, vcc
	v_cndmask_b32_e32 v248, v132, v133, vcc
	v_cndmask_b32_e32 v249, v133, v130, vcc
	v_cndmask_b32_e64 v130, v246, v248, s[98:99]
	v_cndmask_b32_e64 v131, v247, v249, s[98:99]
	v_cndmask_b32_e64 v132, v248, v246, s[98:99]
; __device__ __forceinline__ void na2_task(const Params& p_, int l, int task, unsigned char* lds) {
;     ...
;     { const int pair = lane & 31, chunk = (lane >> 5) + 2 * (w & 3);
;       unsigned* VTd = (unsigned*)(VT + (size_t)hh * 64 * 520);
;       u32x4 xs[8], ys[8];
; #pragma unroll
;       for (int a = 0; a < 8; ++a) { const size_t tok = (size_t)b * SEQ + (row_start + a) * 64 + 2 * pair;
;           const bf16* src = Z + tok * DIN + 4 * DG + h * 64 + chunk * 8; xs[a] = *(const u32x4*)src; ys[a] = *(const u32x4*)(src + DIN); }
;       asm volatile("" ::: "memory");
; #pragma unroll
;       for (int a = 0; a < 8; ++a) { const unsigned xu[4] = {xs[a].x, xs[a].y, xs[a].z, xs[a].w}, yu[4] = {ys[a].x, ys[a].y, ys[a].z, ys[a].w};
; #pragma unroll
;           for (int i = 0; i < 4; ++i) { VTd[(chunk * 8 + 2 * i) * 260 + a * 32 + pair] = (xu[i] & 0xffffu) | (yu[i] << 16);
;               VTd[(chunk * 8 + 2 * i + 1) * 260 + a * 32 + pair] = (xu[i] >> 16) | (yu[i] & 0xffff0000u); } } }
	v_cndmask_b32_e64 v133, v249, v247, s[98:99]
	v_cndmask_b32_e32 v246, v134, v135, vcc
	v_cndmask_b32_e32 v247, v135, v136, vcc
	v_cndmask_b32_e32 v248, v136, v137, vcc
	v_cndmask_b32_e32 v249, v137, v134, vcc
	v_cndmask_b32_e64 v134, v246, v248, s[98:99]
	v_cndmask_b32_e64 v135, v247, v249, s[98:99]
	v_cndmask_b32_e64 v136, v248, v246, s[98:99]
	v_cndmask_b32_e64 v137, v249, v247, s[98:99]
	v_cndmask_b32_e32 v246, v138, v139, vcc
	v_cndmask_b32_e32 v247, v139, v140, vcc
	v_cndmask_b32_e32 v248, v140, v141, vcc
	v_cndmask_b32_e32 v249, v141, v138, vcc
	v_cndmask_b32_e64 v138, v246, v248, s[98:99]
	v_cndmask_b32_e64 v139, v247, v249, s[98:99]
	v_cndmask_b32_e64 v140, v248, v246, s[98:99]
	v_cndmask_b32_e64 v141, v249, v247, s[98:99]
	v_cndmask_b32_e32 v246, v142, v143, vcc
	v_cndmask_b32_e32 v247, v143, v144, vcc
	v_cndmask_b32_e32 v248, v144, v145, vcc
	v_cndmask_b32_e32 v249, v145, v142, vcc
	v_cndmask_b32_e64 v142, v246, v248, s[98:99]
	v_cndmask_b32_e64 v143, v247, v249, s[98:99]
	v_cndmask_b32_e64 v144, v248, v246, s[98:99]
	v_cndmask_b32_e64 v145, v249, v247, s[98:99]
	v_cndmask_b32_e32 v246, v160, v161, vcc
	v_cndmask_b32_e32 v247, v161, v162, vcc
	v_cndmask_b32_e32 v248, v162, v163, vcc
	v_cndmask_b32_e32 v249, v163, v160, vcc
	v_cndmask_b32_e64 v160, v246, v248, s[98:99]
	v_cndmask_b32_e64 v161, v247, v249, s[98:99]
	v_cndmask_b32_e64 v162, v248, v246, s[98:99]
	v_cndmask_b32_e64 v163, v249, v247, s[98:99]
	v_cndmask_b32_e32 v246, v164, v165, vcc
	v_cndmask_b32_e32 v247, v165, v166, vcc
	v_cndmask_b32_e32 v248, v166, v167, vcc
	v_cndmask_b32_e32 v249, v167, v164, vcc
	v_cndmask_b32_e64 v164, v246, v248, s[98:99]
	v_cndmask_b32_e64 v165, v247, v249, s[98:99]
	v_cndmask_b32_e64 v166, v248, v246, s[98:99]
	v_cndmask_b32_e64 v167, v249, v247, s[98:99]
	v_cndmask_b32_e32 v246, v168, v169, vcc
	v_cndmask_b32_e32 v247, v169, v170, vcc
	v_cndmask_b32_e32 v248, v170, v171, vcc
	v_cndmask_b32_e32 v249, v171, v168, vcc
	v_cndmask_b32_e64 v168, v246, v248, s[98:99]
	v_cndmask_b32_e64 v169, v247, v249, s[98:99]
	v_cndmask_b32_e64 v170, v248, v246, s[98:99]
	v_cndmask_b32_e64 v171, v249, v247, s[98:99]
	s_waitcnt lgkmcnt(0)
	v_lshlrev_b32_e32 v88, 2, v172
	v_mul_u32_u24_e32 v172, 0x104, v173
	v_mad_i32_i24 v81, v93, s13, 0
	v_lshlrev_b32_e32 v172, 2, v172
	v_add3_u32 v173, v81, v88, v172
	v_and_b32_e32 v248, 3, v147
	v_add_u32_e32 v249, 0, v248
	v_and_b32_e32 v249, 3, v249
	v_mul_u32_u24_e32 v249, 0x820, v249
	v_add_u32_e32 v238, v173, v249
	v_add_u32_e32 v239, 0x410, v238
	v_add_u32_e32 v249, 1, v248
	v_and_b32_e32 v249, 3, v249
	v_mul_u32_u24_e32 v249, 0x820, v249
	v_add_u32_e32 v240, v173, v249
	v_add_u32_e32 v241, 0x410, v240
	v_add_u32_e32 v249, 2, v248
	v_and_b32_e32 v249, 3, v249
	v_mul_u32_u24_e32 v249, 0x820, v249
	v_add_u32_e32 v242, v173, v249
	v_add_u32_e32 v243, 0x410, v242
	v_add_u32_e32 v249, 3, v248
	v_and_b32_e32 v249, 3, v249
	v_mul_u32_u24_e32 v249, 0x820, v249
	v_add_u32_e32 v244, v173, v249
	v_add_u32_e32 v245, 0x410, v244
	s_mov_b32 s98, 0x5040100
	s_mov_b32 s99, 0x7060302
	v_perm_b32 v246, v98, v94, s98
	v_perm_b32 v247, v106, v102, s98
	ds_write2_b32 v238, v246, v247 offset1:32
	v_perm_b32 v94, v98, v94, s99
	v_perm_b32 v102, v106, v102, s99
	ds_write2_b32 v239, v94, v102 offset1:32
	v_perm_b32 v248, v99, v95, s98
	v_perm_b32 v249, v107, v103, s98
	ds_write2_b32 v240, v248, v249 offset1:32
	v_perm_b32 v95, v99, v95, s99
	v_perm_b32 v103, v107, v103, s99
	ds_write2_b32 v241, v95, v103 offset1:32
	v_perm_b32 v246, v100, v96, s98
	v_perm_b32 v247, v108, v104, s98
	ds_write2_b32 v242, v246, v247 offset1:32
	v_perm_b32 v96, v100, v96, s99
	v_perm_b32 v104, v108, v104, s99
	ds_write2_b32 v243, v96, v104 offset1:32
	v_perm_b32 v248, v101, v97, s98
	v_perm_b32 v249, v109, v105, s98
	ds_write2_b32 v244, v248, v249 offset1:32
	v_perm_b32 v97, v101, v97, s99
	v_perm_b32 v105, v109, v105, s99
	ds_write2_b32 v245, v97, v105 offset1:32
	v_perm_b32 v246, v114, v110, s98
	v_perm_b32 v247, v122, v118, s98
	ds_write2_b32 v238, v246, v247 offset0:64 offset1:96
	v_perm_b32 v110, v114, v110, s99
	v_perm_b32 v118, v122, v118, s99
	ds_write2_b32 v239, v110, v118 offset0:64 offset1:96
	v_perm_b32 v248, v115, v111, s98
	v_perm_b32 v249, v123, v119, s98
	ds_write2_b32 v240, v248, v249 offset0:64 offset1:96
	v_perm_b32 v111, v115, v111, s99
	v_perm_b32 v119, v123, v119, s99
	ds_write2_b32 v241, v111, v119 offset0:64 offset1:96
	v_perm_b32 v246, v116, v112, s98
	v_perm_b32 v247, v124, v120, s98
	ds_write2_b32 v242, v246, v247 offset0:64 offset1:96
	v_perm_b32 v112, v116, v112, s99
	v_perm_b32 v120, v124, v120, s99
	ds_write2_b32 v243, v112, v120 offset0:64 offset1:96
	v_perm_b32 v248, v117, v113, s98
	v_perm_b32 v249, v125, v121, s98
	ds_write2_b32 v244, v248, v249 offset0:64 offset1:96
	v_perm_b32 v113, v117, v113, s99
	v_perm_b32 v121, v125, v121, s99
	ds_write2_b32 v245, v113, v121 offset0:64 offset1:96
	v_perm_b32 v246, v130, v126, s98
	v_perm_b32 v247, v138, v134, s98
	ds_write2_b32 v238, v246, v247 offset0:128 offset1:160
	v_perm_b32 v126, v130, v126, s99
	v_perm_b32 v134, v138, v134, s99
	ds_write2_b32 v239, v126, v134 offset0:128 offset1:160
	v_perm_b32 v248, v131, v127, s98
	v_perm_b32 v249, v139, v135, s98
	ds_write2_b32 v240, v248, v249 offset0:128 offset1:160
	v_perm_b32 v127, v131, v127, s99
	v_perm_b32 v135, v139, v135, s99
	ds_write2_b32 v241, v127, v135 offset0:128 offset1:160
	v_perm_b32 v246, v132, v128, s98
	v_perm_b32 v247, v140, v136, s98
	ds_write2_b32 v242, v246, v247 offset0:128 offset1:160
	v_perm_b32 v128, v132, v128, s99
	v_perm_b32 v136, v140, v136, s99
	ds_write2_b32 v243, v128, v136 offset0:128 offset1:160
; #define MFMA16(a, b, c) __builtin_amdgcn_mfma_f32_16x16x32_bf16(a, b, c, 0, 0, 0)
; __device__ __forceinline__ void na2_task(const Params& p_, int l, int task, unsigned char* lds) {
;     ...
;     for (int i = tid; i < 930; i += NTHR) BI[i] = p.na_bias[(size_t)(l * 8 + hp * 2) * 465 + i];
;     { const int pair = lane & 31, chunk = (lane >> 5) + 2 * (w & 3);
;       unsigned* VTd = (unsigned*)(VT + (size_t)hh * 64 * 520);
;       u32x4 xs[8], ys[8];
; #pragma unroll
;       for (int a = 0; a < 8; ++a) { const size_t tok = (size_t)b * SEQ + (row_start + a) * 64 + 2 * pair;
;           const bf16* src = Z + tok * DIN + 4 * DG + h * 64 + chunk * 8; xs[a] = *(const u32x4*)src; ys[a] = *(const u32x4*)(src + DIN); }
;       asm volatile("" ::: "memory");
; #pragma unroll
;       for (int a = 0; a < 8; ++a) { const unsigned xu[4] = {xs[a].x, xs[a].y, xs[a].z, xs[a].w}, yu[4] = {ys[a].x, ys[a].y, ys[a].z, ys[a].w};
; #pragma unroll
;           for (int i = 0; i < 4; ++i) { VTd[(chunk * 8 + 2 * i) * 260 + a * 32 + pair] = (xu[i] & 0xffffu) | (yu[i] << 16);
;               VTd[(chunk * 8 + 2 * i + 1) * 260 + a * 32 + pair] = (xu[i] >> 16) | (yu[i] & 0xffff0000u); } } }
;     __syncthreads();
;     const int col_start = min(max(c - 8, 0), 48);
;     const float* bi = BI + hh * 465;
;     float sc[16][4]; float mx = -1e30f;
; #pragma unroll
;     for (int hf = 0; hf < 2; ++hf) {
;         if (hf == 1) {
; #pragma unroll
;             for (int i = 0; i < 8; ++i) { const int a = 4 + i / 2, ci = i % 2;
;                 const size_t ktok = (size_t)b * SEQ + (row_start + a) * 64 + kst + 16 * ci + fr;
; #pragma unroll
;                 for (int ks = 0; ks < 2; ++ks) kfr[i][ks] = *(const bf16x8v*)(Z + ktok * DIN + 3 * DG + h * 64 + 32 * ks + 8 * fq); }
;             asm volatile("" ::: "memory");
;         }
; #pragma unroll
;         for (int i = 0; i < 8; ++i) { const int a = 4 * hf + i / 2, ci = i % 2, kt = a * 2 + ci;
;             f32x4 acc = {0.f, 0.f, 0.f, 0.f};
; #pragma unroll
;             for (int ks = 0; ks < 2; ++ks) acc = MFMA16(kfr[i][ks], qf[ks], acc);
;             const int dr = row_start + a - rq;
; #pragma unroll
;             for (int r = 0; r < 4; ++r) { const int kc = kst + 16 * ci + 4 * fq + r, rel = kc - col_start, dc = kc - c;
;                 float v = acc[r] * 0.125f + bi[(dr + 7) * 31 + min(max(dc + 15, 0), 30)];
	v_perm_b32 v248, v133, v129, s98
	v_perm_b32 v249, v141, v137, s98
	ds_write2_b32 v244, v248, v249 offset0:128 offset1:160
	v_perm_b32 v129, v133, v129, s99
	v_perm_b32 v137, v141, v137, s99
	ds_write2_b32 v245, v129, v137 offset0:128 offset1:160
	v_perm_b32 v246, v160, v142, s98
	v_perm_b32 v247, v168, v164, s98
	ds_write2_b32 v238, v246, v247 offset0:192 offset1:224
	v_perm_b32 v142, v160, v142, s99
	v_perm_b32 v164, v168, v164, s99
	ds_write2_b32 v239, v142, v164 offset0:192 offset1:224
	v_perm_b32 v248, v161, v143, s98
	v_perm_b32 v249, v169, v165, s98
	ds_write2_b32 v240, v248, v249 offset0:192 offset1:224
	v_perm_b32 v143, v161, v143, s99
	v_perm_b32 v165, v169, v165, s99
	ds_write2_b32 v241, v143, v165 offset0:192 offset1:224
	v_perm_b32 v246, v162, v144, s98
	v_perm_b32 v247, v170, v166, s98
	ds_write2_b32 v242, v246, v247 offset0:192 offset1:224
	v_perm_b32 v144, v162, v144, s99
	v_perm_b32 v166, v170, v166, s99
	ds_write2_b32 v243, v144, v166 offset0:192 offset1:224
	v_perm_b32 v248, v163, v145, s98
	v_perm_b32 v249, v171, v167, s98
	ds_write2_b32 v244, v248, v249 offset0:192 offset1:224
	v_perm_b32 v145, v163, v145, s99
	v_perm_b32 v167, v171, v167, s99
	ds_write2_b32 v245, v145, v167 offset0:192 offset1:224
	v_mfma_f32_16x16x32_bf16 v[62:65], v[62:65], v[6:9], 0
	s_sub_i32 s9, s12, s9
	v_mfma_f32_16x16x32_bf16 v[70:73], v[70:73], v[6:9], 0
	v_lshl_add_u32 v168, v92, 2, v80
	s_mulk_i32 s9, 0x7c
	v_add_u32_e32 v169, 16, v168
	s_add_i32 s9, s9, 0
	v_sub_u32_e32 v88, v169, v91
	s_add_i32 s9, s9, 0x20800
	v_mfma_f32_16x16x32_bf16 v[58:61], v[58:61], v[2:5], v[62:65]
	v_add_u32_e32 v173, 17, v168
	v_add_u32_e32 v174, 18, v168
	v_or_b32_e32 v170, 1, v168
	v_max_i32_e32 v62, -15, v88
	v_mfma_f32_16x16x32_bf16 v[94:97], v[66:69], v[2:5], v[70:73]
	v_mov_b32_e32 v66, s9
	s_movk_i32 s9, 0x744
	v_add_u32_e32 v62, 15, v62
	v_mad_i32_i24 v98, v93, s9, v66
	v_min_u32_e32 v62, 30, v62
	v_lshl_add_u32 v103, v62, 2, v98
	v_sub_u32_e32 v62, v173, v91
	v_mfma_f32_16x16x32_bf16 v[18:21], v[18:21], v[6:9], 0
	v_max_i32_e32 v62, -15, v62
	v_add_u32_e32 v62, 15, v62
	v_min_u32_e32 v62, 30, v62
	v_lshl_add_u32 v104, v62, 2, v98
	v_mfma_f32_16x16x32_bf16 v[62:65], v[10:13], v[2:5], v[18:21]
	v_sub_u32_e32 v10, v174, v91
	v_or_b32_e32 v171, 2, v168
	v_or_b32_e32 v172, 3, v168
	v_max_i32_e32 v18, -15, v10
	v_mfma_f32_16x16x32_bf16 v[10:13], v[38:41], v[6:9], 0
	v_add_u32_e32 v175, 19, v168
	v_sub_u32_e32 v66, v168, v91
	v_sub_u32_e32 v68, v170, v91
	v_mfma_f32_16x16x32_bf16 v[38:41], v[22:25], v[2:5], v[10:13]
	v_sub_u32_e32 v70, v171, v91
	v_sub_u32_e32 v72, v172, v91
	v_sub_u32_e32 v19, v175, v91
	v_mfma_f32_16x16x32_bf16 v[10:13], v[54:57], v[6:9], 0
	v_max_i32_e32 v66, -15, v66
	v_max_i32_e32 v68, -15, v68
	v_max_i32_e32 v70, -15, v70
	v_mfma_f32_16x16x32_bf16 v[42:45], v[42:45], v[2:5], v[10:13]
	v_max_i32_e32 v72, -15, v72
	v_max_i32_e32 v19, -15, v19
	v_add_u32_e32 v66, 15, v66
	v_mfma_f32_16x16x32_bf16 v[10:13], v[46:49], v[6:9], 0
	v_add_u32_e32 v68, 15, v68
	v_add_u32_e32 v70, 15, v70
	v_add_u32_e32 v72, 15, v72
	v_mfma_f32_16x16x32_bf16 v[46:49], v[30:33], v[2:5], v[10:13]
	v_add_u32_e32 v18, 15, v18
	v_add_u32_e32 v19, 15, v19
	v_lshlrev_b32_e32 v0, 3, v92
	v_mfma_f32_16x16x32_bf16 v[10:13], v[26:29], v[6:9], 0
	v_min_u32_e32 v66, 30, v66
	v_min_u32_e32 v68, 30, v68
	v_min_u32_e32 v70, 30, v70
	v_mfma_f32_16x16x32_bf16 v[54:57], v[14:17], v[2:5], v[10:13]
	v_min_u32_e32 v72, 30, v72
	v_min_u32_e32 v18, 30, v18
	v_min_u32_e32 v19, 30, v19
	v_mfma_f32_16x16x32_bf16 v[10:13], v[50:53], v[6:9], 0
	v_lshl_add_u32 v99, v66, 2, v98
	v_lshl_add_u32 v100, v68, 2, v98
	v_lshl_add_u32 v101, v70, 2, v98
	v_mfma_f32_16x16x32_bf16 v[50:53], v[34:37], v[2:5], v[10:13]
	v_lshl_add_u32 v102, v72, 2, v98
	v_lshl_add_u32 v18, v18, 2, v98
	v_lshl_add_u32 v19, v19, 2, v98
	s_nop 0
	v_lshl_add_u64 v[10:11], v[82:83], 0, s[44:45]
	v_mad_u64_u32 v[12:13], s[12:13], v10, s75, v[86:87]
	v_mov_b32_e32 v10, v13
	v_mad_u64_u32 v[10:11], s[12:13], v11, s75, v[10:11]
	v_mov_b32_e32 v13, v10
	v_lshl_add_u64 v[10:11], v[12:13], 0, v[76:77]
	v_mov_b32_e32 v12, v252
	v_mov_b32_e32 v13, v1
	v_add_u32_e32 v176, 0x400, v99
	v_add_u32_e32 v177, 0x400, v100
	v_add_u32_e32 v197, 0x400, v101
	v_add_u32_e32 v198, 0x400, v102
	v_add_u32_e32 v199, 0x400, v103
	v_add_u32_e32 v200, 0x400, v104
	v_add_u32_e32 v201, 0x400, v18
	v_add_u32_e32 v202, 0x400, v19
	v_lshl_add_u64 v[10:11], v[10:11], 0, v[12:13]
	ds_write_b32 v204, v203
	ds_write_b32 v205, v209
	s_waitcnt lgkmcnt(0)
	s_barrier
; #define MFMA16(a, b, c) __builtin_amdgcn_mfma_f32_16x16x32_bf16(a, b, c, 0, 0, 0)
; __device__ __forceinline__ void na2_task(const Params& p_, int l, int task, unsigned char* lds) {
;     ...
;     const int col_start = min(max(c - 8, 0), 48);
;     const float* bi = BI + hh * 465;
;     float sc[16][4]; float mx = -1e30f;
; #pragma unroll
;     for (int hf = 0; hf < 2; ++hf) {
;         if (hf == 1) {
; #pragma unroll
;             for (int i = 0; i < 8; ++i) { const int a = 4 + i / 2, ci = i % 2;
;                 const size_t ktok = (size_t)b * SEQ + (row_start + a) * 64 + kst + 16 * ci + fr;
; #pragma unroll
;                 for (int ks = 0; ks < 2; ++ks) kfr[i][ks] = *(const bf16x8v*)(Z + ktok * DIN + 3 * DG + h * 64 + 32 * ks + 8 * fq); }
;             asm volatile("" ::: "memory");
;         }
; #pragma unroll
;         for (int i = 0; i < 8; ++i) { const int a = 4 * hf + i / 2, ci = i % 2, kt = a * 2 + ci;
;             f32x4 acc = {0.f, 0.f, 0.f, 0.f};
; #pragma unroll
;             for (int ks = 0; ks < 2; ++ks) acc = MFMA16(kfr[i][ks], qf[ks], acc);
;             const int dr = row_start + a - rq;
; #pragma unroll
;             for (int r = 0; r < 4; ++r) { const int kc = kst + 16 * ci + 4 * fq + r, rel = kc - col_start, dc = kc - c;
;                 float v = acc[r] * 0.125f + bi[(dr + 7) * 31 + min(max(dc + 15, 0), 30)];
;                 v = (rel >= 0 && rel < 16) ? v : -1e30f; sc[kt][r] = v; mx = fmaxf(mx, v); } }
	ds_read2_b32 v[66:67], v99 offset0:217 offset1:248
	ds_read2_b32 v[68:69], v100 offset0:217 offset1:248
	ds_read2_b32 v[70:71], v101 offset0:217 offset1:248
	ds_read2_b32 v[72:73], v102 offset0:217 offset1:248
	ds_read2_b32 v[88:89], v103 offset0:217 offset1:248
	ds_read2_b32 v[92:93], v104 offset0:217 offset1:248
	ds_read2_b32 v[134:135], v18 offset0:217 offset1:248
	ds_read2_b32 v[136:137], v19 offset0:217 offset1:248
	ds_read2_b32 v[138:139], v176 offset0:23 offset1:54
	ds_read2_b32 v[140:141], v177 offset0:23 offset1:54
	ds_read2_b32 v[142:143], v197 offset0:23 offset1:54
	ds_read2_b32 v[144:145], v198 offset0:23 offset1:54
	ds_read2_b32 v[160:161], v199 offset0:23 offset1:54
	ds_read2_b32 v[162:163], v200 offset0:23 offset1:54
	ds_read2_b32 v[164:165], v201 offset0:23 offset1:54
	ds_read2_b32 v[166:167], v202 offset0:23 offset1:54
	s_nop 0
	s_nop 0
	v_lshl_add_u64 v[10:11], v[84:85], 0, s[44:45]
	v_mad_u64_u32 v[14:15], s[12:13], v10, s75, v[86:87]
	v_mov_b32_e32 v10, v15
	v_mad_u64_u32 v[10:11], s[12:13], v11, s75, v[10:11]
	v_mov_b32_e32 v15, v10
	v_lshl_add_u64 v[10:11], v[14:15], 0, v[76:77]
	v_lshl_add_u64 v[10:11], v[10:11], 0, v[12:13]
	s_nop 0
	s_nop 0
	v_lshl_add_u64 v[10:11], v[82:83], 0, s[42:43]
	v_mad_u64_u32 v[14:15], s[12:13], v10, s75, v[86:87]
	v_mov_b32_e32 v10, v15
	v_mad_u64_u32 v[10:11], s[12:13], v11, s75, v[10:11]
	v_mov_b32_e32 v15, v10
	v_lshl_add_u64 v[10:11], v[14:15], 0, v[76:77]
	v_lshl_add_u64 v[10:11], v[10:11], 0, v[12:13]
	s_nop 0
	s_nop 0
	v_lshl_add_u64 v[10:11], v[84:85], 0, s[42:43]
	v_mad_u64_u32 v[14:15], s[12:13], v10, s75, v[86:87]
	v_mov_b32_e32 v10, v15
	v_mad_u64_u32 v[10:11], s[12:13], v11, s75, v[10:11]
	v_mov_b32_e32 v15, v10
	v_lshl_add_u64 v[10:11], v[14:15], 0, v[76:77]
	v_lshl_add_u64 v[10:11], v[10:11], 0, v[12:13]
	s_nop 0
	global_load_dwordx4 v[126:129], v[10:11], off offset:3136
	v_lshl_add_u64 v[10:11], v[82:83], 0, s[40:41]
	v_mad_u64_u32 v[14:15], s[12:13], v10, s75, v[86:87]
	v_mov_b32_e32 v10, v15
	v_mad_u64_u32 v[10:11], s[12:13], v11, s75, v[10:11]
	v_mov_b32_e32 v15, v10
	v_lshl_add_u64 v[10:11], v[14:15], 0, v[76:77]
	v_lshl_add_u64 v[10:11], v[10:11], 0, v[12:13]
	global_load_dwordx4 v[130:133], v[10:11], off offset:3072
	global_load_dwordx4 v[34:37], v[10:11], off offset:3136
	v_lshl_add_u64 v[10:11], v[84:85], 0, s[40:41]
	v_mad_u64_u32 v[14:15], s[12:13], v10, s75, v[86:87]
	v_mov_b32_e32 v10, v15
	v_mad_u64_u32 v[10:11], s[12:13], v11, s75, v[10:11]
	v_mov_b32_e32 v15, v10
	v_lshl_add_u64 v[10:11], v[14:15], 0, v[76:77]
	v_lshl_add_u64 v[10:11], v[10:11], 0, v[12:13]
	global_load_dwordx4 v[30:33], v[10:11], off offset:3072
	global_load_dwordx4 v[26:29], v[10:11], off offset:3136
	v_lshl_add_u64 v[10:11], v[82:83], 0, s[24:25]
	v_mad_u64_u32 v[14:15], s[12:13], v10, s75, v[86:87]
	v_mov_b32_e32 v10, v15
	v_mad_u64_u32 v[10:11], s[12:13], v11, s75, v[10:11]
	v_mov_b32_e32 v15, v10
	v_lshl_add_u64 v[10:11], v[14:15], 0, v[76:77]
	v_lshl_add_u64 v[10:11], v[10:11], 0, v[12:13]
	global_load_dwordx4 v[22:25], v[10:11], off offset:3072
	global_load_dwordx4 v[18:21], v[10:11], off offset:3136
	v_lshl_add_u64 v[10:11], v[84:85], 0, s[24:25]
	v_mad_u64_u32 v[14:15], s[12:13], v10, s75, v[86:87]
	v_mov_b32_e32 v10, v15
	v_mad_u64_u32 v[10:11], s[12:13], v11, s75, v[10:11]
	v_mov_b32_e32 v15, v10
	v_sub_u32_e64 v82, v91, 8 clamp
	v_lshl_add_u64 v[10:11], v[14:15], 0, v[76:77]
	v_min_u32_e32 v82, 48, v82
	v_lshl_add_u64 v[10:11], v[10:11], 0, v[12:13]
	v_sub_u32_e32 v84, v171, v82
	global_load_dwordx4 v[14:17], v[10:11], off offset:3072
	s_nop 0
	global_load_dwordx4 v[10:13], v[10:11], off offset:3136
	v_cmp_gt_u32_e64 s[46:47], 16, v84
	v_sub_u32_e32 v84, v172, v82
	v_sub_u32_e32 v83, v168, v82
	v_cmp_gt_u32_e64 s[42:43], 16, v84
	v_sub_u32_e32 v84, v169, v82
	v_cmp_gt_u32_e32 vcc, 16, v83
	v_sub_u32_e32 v83, v170, v82
	s_waitcnt lgkmcnt(11)
	v_fmamk_f32 v58, v58, 0x3e000000, v88
	v_cmp_gt_u32_e64 s[44:45], 16, v84
	v_fmamk_f32 v66, v94, 0x3e000000, v66
	v_fmamk_f32 v68, v95, 0x3e000000, v68
	v_cmp_gt_u32_e64 s[40:41], 16, v83
	v_cndmask_b32_e64 v84, v194, v58, s[44:45]
	v_sub_u32_e32 v58, v173, v82
	v_cndmask_b32_e32 v66, v194, v66, vcc
	v_cndmask_b32_e64 v68, v194, v68, s[40:41]
	s_mov_b32 s9, 0xf149f2ca
	v_fmamk_f32 v70, v96, 0x3e000000, v70
	v_fmamk_f32 v72, v97, 0x3e000000, v72
	s_waitcnt lgkmcnt(10)
	v_fmamk_f32 v59, v59, 0x3e000000, v92
	v_cmp_gt_u32_e64 s[48:49], 16, v58
	v_max3_f32 v83, v66, s9, v68
	v_cndmask_b32_e64 v70, v194, v70, s[46:47]
	v_cndmask_b32_e64 v72, v194, v72, s[42:43]
	v_cndmask_b32_e64 v85, v194, v59, s[48:49]
	v_sub_u32_e32 v59, v174, v82
	v_max3_f32 v83, v83, v70, v72
	s_waitcnt lgkmcnt(9)
	v_fmamk_f32 v60, v60, 0x3e000000, v134
	v_cmp_gt_u32_e64 s[50:51], 16, v59
	v_sub_u32_e32 v59, v175, v82
	v_max3_f32 v58, v83, v84, v85
	v_cndmask_b32_e64 v83, v194, v60, s[50:51]
	s_waitcnt lgkmcnt(8)
	v_fmamk_f32 v60, v61, 0x3e000000, v136
	v_cmp_gt_u32_e64 s[52:53], 16, v59
	v_fmac_f32_e32 v67, 0x3e000000, v62
	v_fmac_f32_e32 v69, 0x3e000000, v63
	v_cndmask_b32_e64 v82, v194, v60, s[52:53]
	v_fmac_f32_e32 v93, 0x3e000000, v39
	s_waitcnt lgkmcnt(7)
	v_fmamk_f32 v39, v42, 0x3e000000, v138
	v_max3_f32 v58, v58, v83, v82
	v_cndmask_b32_e32 v62, v194, v67, vcc
	v_cndmask_b32_e64 v63, v194, v69, s[40:41]
	v_fmac_f32_e32 v71, 0x3e000000, v64
	v_fmac_f32_e32 v73, 0x3e000000, v65
	v_fmac_f32_e32 v89, 0x3e000000, v38
	v_cndmask_b32_e32 v88, v194, v39, vcc
	s_waitcnt lgkmcnt(6)
	v_fmamk_f32 v39, v43, 0x3e000000, v140
	v_max3_f32 v58, v58, v62, v63
	v_cndmask_b32_e64 v67, v194, v71, s[46:47]
	v_cndmask_b32_e64 v69, v194, v73, s[42:43]
	v_cndmask_b32_e64 v71, v194, v89, s[44:45]
	v_cndmask_b32_e64 v89, v194, v39, s[40:41]
	s_waitcnt lgkmcnt(5)
; #define MFMA16(a, b, c) __builtin_amdgcn_mfma_f32_16x16x32_bf16(a, b, c, 0, 0, 0)
; __device__ __forceinline__ void na2_task(const Params& p_, int l, int task, unsigned char* lds) {
;     ...
;     for (int hf = 0; hf < 2; ++hf) {
;         if (hf == 1) {
; #pragma unroll
;             for (int i = 0; i < 8; ++i) { const int a = 4 + i / 2, ci = i % 2;
;                 const size_t ktok = (size_t)b * SEQ + (row_start + a) * 64 + kst + 16 * ci + fr;
; #pragma unroll
;                 for (int ks = 0; ks < 2; ++ks) kfr[i][ks] = *(const bf16x8v*)(Z + ktok * DIN + 3 * DG + h * 64 + 32 * ks + 8 * fq); }
;             asm volatile("" ::: "memory");
;         }
; #pragma unroll
;         for (int i = 0; i < 8; ++i) { const int a = 4 * hf + i / 2, ci = i % 2, kt = a * 2 + ci;
;             f32x4 acc = {0.f, 0.f, 0.f, 0.f};
; #pragma unroll
;             for (int ks = 0; ks < 2; ++ks) acc = MFMA16(kfr[i][ks], qf[ks], acc);
;             const int dr = row_start + a - rq;
; #pragma unroll
;             for (int r = 0; r < 4; ++r) { const int kc = kst + 16 * ci + 4 * fq + r, rel = kc - col_start, dc = kc - c;
;                 float v = acc[r] * 0.125f + bi[(dr + 7) * 31 + min(max(dc + 15, 0), 30)];
;                 v = (rel >= 0 && rel < 16) ? v : -1e30f; sc[kt][r] = v; mx = fmaxf(mx, v); } }
	v_fmamk_f32 v39, v44, 0x3e000000, v142
	v_max3_f32 v58, v58, v67, v69
	v_cndmask_b32_e64 v73, v194, v93, s[48:49]
	v_fmac_f32_e32 v135, 0x3e000000, v40
	v_fmac_f32_e32 v137, 0x3e000000, v41
	v_cndmask_b32_e64 v91, v194, v39, s[46:47]
	s_waitcnt lgkmcnt(4)
	v_fmamk_f32 v39, v45, 0x3e000000, v144
	v_max3_f32 v38, v58, v71, v73
	v_cndmask_b32_e64 v86, v194, v135, s[50:51]
	v_cndmask_b32_e64 v87, v194, v137, s[52:53]
	v_cndmask_b32_e64 v92, v194, v39, s[42:43]
	s_waitcnt lgkmcnt(3)
	v_fmamk_f32 v39, v46, 0x3e000000, v160
	v_max3_f32 v38, v38, v86, v87
	v_cndmask_b32_e64 v93, v194, v39, s[44:45]
	s_waitcnt lgkmcnt(2)
	v_fmamk_f32 v39, v47, 0x3e000000, v162
	v_max3_f32 v38, v38, v88, v89
	v_cndmask_b32_e64 v94, v194, v39, s[48:49]
	s_waitcnt lgkmcnt(1)
	v_fmamk_f32 v39, v48, 0x3e000000, v164
	v_max3_f32 v38, v38, v91, v92
	v_cndmask_b32_e64 v95, v194, v39, s[50:51]
	s_waitcnt lgkmcnt(0)
	v_fmamk_f32 v39, v49, 0x3e000000, v166
	v_max3_f32 v38, v38, v93, v94
	v_cndmask_b32_e64 v96, v194, v39, s[52:53]
	v_fmac_f32_e32 v139, 0x3e000000, v54
	v_fmac_f32_e32 v141, 0x3e000000, v55
	v_max3_f32 v38, v38, v95, v96
	v_cndmask_b32_e32 v97, v194, v139, vcc
	v_cndmask_b32_e64 v134, v194, v141, s[40:41]
	v_fmac_f32_e32 v143, 0x3e000000, v56
	v_fmac_f32_e32 v145, 0x3e000000, v57
	v_max3_f32 v38, v38, v97, v134
	v_cndmask_b32_e64 v135, v194, v143, s[46:47]
	v_cndmask_b32_e64 v136, v194, v145, s[42:43]
	v_fmac_f32_e32 v161, 0x3e000000, v50
	v_fmac_f32_e32 v163, 0x3e000000, v51
	v_max3_f32 v38, v38, v135, v136
	v_cndmask_b32_e64 v137, v194, v161, s[44:45]
	v_cndmask_b32_e64 v138, v194, v163, s[48:49]
	v_max3_f32 v42, v38, v137, v138
	s_waitcnt vmcnt(0)
	ds_bpermute_b32 v98, v251, v210
	ds_bpermute_b32 v99, v251, v211
	ds_bpermute_b32 v100, v251, v212
	ds_bpermute_b32 v101, v251, v213
	ds_bpermute_b32 v102, v251, v214
	ds_bpermute_b32 v103, v251, v215
	ds_bpermute_b32 v104, v251, v216
	ds_bpermute_b32 v105, v251, v217
	ds_bpermute_b32 v106, v251, v218
	ds_bpermute_b32 v107, v251, v219
	ds_bpermute_b32 v108, v251, v220
	ds_bpermute_b32 v109, v251, v221
	ds_bpermute_b32 v110, v251, v222
	ds_bpermute_b32 v111, v251, v223
	ds_bpermute_b32 v112, v251, v224
	ds_bpermute_b32 v113, v251, v225
	ds_bpermute_b32 v114, v251, v226
	ds_bpermute_b32 v115, v251, v227
	ds_bpermute_b32 v116, v251, v228
	ds_bpermute_b32 v117, v251, v229
	ds_bpermute_b32 v118, v251, v230
	ds_bpermute_b32 v119, v251, v231
	ds_bpermute_b32 v120, v251, v232
	ds_bpermute_b32 v121, v251, v233
	ds_bpermute_b32 v122, v251, v234
	ds_bpermute_b32 v123, v251, v235
	ds_bpermute_b32 v124, v251, v236
	ds_bpermute_b32 v125, v251, v237
	ds_bpermute_b32 v126, v251, v126
	ds_bpermute_b32 v127, v251, v127
	ds_bpermute_b32 v128, v251, v128
	ds_bpermute_b32 v129, v251, v129
	ds_bpermute_b32 v130, v251, v130
	ds_bpermute_b32 v131, v251, v131
	ds_bpermute_b32 v132, v251, v132
	ds_bpermute_b32 v133, v251, v133
	ds_bpermute_b32 v34, v251, v34
	ds_bpermute_b32 v35, v251, v35
	ds_bpermute_b32 v36, v251, v36
	ds_bpermute_b32 v37, v251, v37
	ds_bpermute_b32 v30, v251, v30
	ds_bpermute_b32 v31, v251, v31
	ds_bpermute_b32 v32, v251, v32
	ds_bpermute_b32 v33, v251, v33
	ds_bpermute_b32 v26, v251, v26
	ds_bpermute_b32 v27, v251, v27
	ds_bpermute_b32 v28, v251, v28
	ds_bpermute_b32 v29, v251, v29
	ds_bpermute_b32 v22, v251, v22
	ds_bpermute_b32 v23, v251, v23
	ds_bpermute_b32 v24, v251, v24
	ds_bpermute_b32 v25, v251, v25
	ds_bpermute_b32 v18, v251, v18
	ds_bpermute_b32 v19, v251, v19
	ds_bpermute_b32 v20, v251, v20
	ds_bpermute_b32 v21, v251, v21
	ds_bpermute_b32 v14, v251, v14
	ds_bpermute_b32 v15, v251, v15
	ds_bpermute_b32 v16, v251, v16
	ds_bpermute_b32 v17, v251, v17
	ds_bpermute_b32 v10, v251, v10
	ds_bpermute_b32 v11, v251, v11
	ds_bpermute_b32 v12, v251, v12
	ds_bpermute_b32 v13, v251, v13
	s_waitcnt lgkmcnt(0)
	v_mfma_f32_16x16x32_bf16 v[38:41], v[98:101], v[6:9], 0
	ds_read2_b32 v[46:47], v176 offset0:85 offset1:116
	ds_read2_b32 v[48:49], v177 offset0:85 offset1:116
	ds_read2_b32 v[50:51], v197 offset0:85 offset1:116
	s_waitcnt vmcnt(14)
	v_mfma_f32_16x16x32_bf16 v[38:41], v[102:105], v[2:5], v[38:41]
	v_fmac_f32_e32 v165, 0x3e000000, v52
	v_fmac_f32_e32 v167, 0x3e000000, v53
	ds_read2_b32 v[52:53], v198 offset0:85 offset1:116
	ds_read2_b32 v[54:55], v199 offset0:85 offset1:116
	ds_read2_b32 v[56:57], v200 offset0:85 offset1:116
	s_waitcnt lgkmcnt(5)
	s_nop 1
	v_fmamk_f32 v38, v38, 0x3e000000, v46
	v_cndmask_b32_e32 v98, v194, v38, vcc
	s_waitcnt lgkmcnt(4)
	v_fmamk_f32 v38, v39, 0x3e000000, v48
	v_cndmask_b32_e64 v48, v194, v38, s[40:41]
	s_waitcnt lgkmcnt(3)
	v_fmamk_f32 v38, v40, 0x3e000000, v50
	v_cndmask_b32_e64 v50, v194, v38, s[46:47]
	s_waitcnt lgkmcnt(2)
	v_fmamk_f32 v38, v41, 0x3e000000, v52
	v_cndmask_b32_e64 v52, v194, v38, s[42:43]
	s_waitcnt vmcnt(13)
	v_mfma_f32_16x16x32_bf16 v[38:41], v[106:109], v[6:9], 0
	v_cndmask_b32_e64 v139, v194, v165, s[50:51]
	v_cndmask_b32_e64 v140, v194, v167, s[52:53]
	ds_read2_b32 v[58:59], v201 offset0:85 offset1:116
	s_waitcnt vmcnt(12)
	v_mfma_f32_16x16x32_bf16 v[38:41], v[110:113], v[2:5], v[38:41]
	v_max3_f32 v42, v42, v139, v140
	ds_read2_b32 v[60:61], v202 offset0:85 offset1:116
	v_max3_f32 v42, v42, v98, v48
	v_max3_f32 v42, v42, v50, v52
	s_waitcnt vmcnt(5)
	v_mfma_f32_16x16x32_bf16 v[30:33], v[30:33], v[6:9], 0
	s_waitcnt lgkmcnt(3)
	s_nop 0
	v_fmamk_f32 v38, v38, 0x3e000000, v54
	v_cndmask_b32_e64 v54, v194, v38, s[44:45]
	s_waitcnt lgkmcnt(2)
	v_fmamk_f32 v38, v39, 0x3e000000, v56
	v_cndmask_b32_e64 v99, v194, v38, s[48:49]
	v_max3_f32 v38, v42, v54, v99
	v_mfma_f32_16x16x32_bf16 v[42:45], v[114:117], v[6:9], 0
	s_waitcnt lgkmcnt(1)
; #define MFMA16(a, b, c) __builtin_amdgcn_mfma_f32_16x16x32_bf16(a, b, c, 0, 0, 0)
; __device__ __forceinline__ void na2_task(const Params& p_, int l, int task, unsigned char* lds) {
;     ...
; #pragma unroll
;         for (int i = 0; i < 8; ++i) { const int a = 4 * hf + i / 2, ci = i % 2, kt = a * 2 + ci;
;             f32x4 acc = {0.f, 0.f, 0.f, 0.f};
; #pragma unroll
;             for (int ks = 0; ks < 2; ++ks) acc = MFMA16(kfr[i][ks], qf[ks], acc);
;             const int dr = row_start + a - rq;
; #pragma unroll
;             for (int r = 0; r < 4; ++r) { const int kc = kst + 16 * ci + 4 * fq + r, rel = kc - col_start, dc = kc - c;
;                 float v = acc[r] * 0.125f + bi[(dr + 7) * 31 + min(max(dc + 15, 0), 30)];
;                 v = (rel >= 0 && rel < 16) ? v : -1e30f; sc[kt][r] = v; mx = fmaxf(mx, v); } }
;     }
;     mx = fmaxf(mx, __shfl_xor(mx, 16)); mx = fmaxf(mx, __shfl_xor(mx, 32));
	v_fmamk_f32 v39, v40, 0x3e000000, v58
	v_cndmask_b32_e64 v100, v194, v39, s[50:51]
	s_waitcnt lgkmcnt(0)
	v_fmamk_f32 v39, v41, 0x3e000000, v60
	v_cndmask_b32_e64 v101, v194, v39, s[52:53]
	v_max3_f32 v46, v38, v100, v101
	v_mfma_f32_16x16x32_bf16 v[38:41], v[118:121], v[2:5], v[42:45]
	v_lshl_add_u64 v[78:79], v[78:79], 0, v[0:1]
	s_mov_b32 s9, 0x12d20000
	v_mfma_f32_16x16x32_bf16 v[42:45], v[122:125], v[6:9], 0
	s_waitcnt vmcnt(4)
	v_mfma_f32_16x16x32_bf16 v[26:29], v[26:29], v[2:5], v[30:33]
	s_nop 2
	v_fmac_f32_e32 v47, 0x3e000000, v38
	v_fmac_f32_e32 v49, 0x3e000000, v39
	v_cndmask_b32_e32 v102, v194, v47, vcc
	v_cndmask_b32_e64 v49, v194, v49, s[40:41]
	v_fmac_f32_e32 v51, 0x3e000000, v40
	v_fmac_f32_e32 v53, 0x3e000000, v41
	v_max3_f32 v38, v46, v102, v49
	v_cndmask_b32_e64 v51, v194, v51, s[46:47]
	v_cndmask_b32_e64 v53, v194, v53, s[42:43]
	v_max3_f32 v46, v38, v51, v53
	v_mfma_f32_16x16x32_bf16 v[38:41], v[126:129], v[2:5], v[42:45]
	s_waitcnt vmcnt(3)
	v_mfma_f32_16x16x32_bf16 v[22:25], v[22:25], v[6:9], 0
	s_waitcnt vmcnt(2)
	v_mfma_f32_16x16x32_bf16 v[18:21], v[18:21], v[2:5], v[22:25]
	s_nop 3
	v_fmac_f32_e32 v55, 0x3e000000, v38
	v_fmac_f32_e32 v57, 0x3e000000, v39
	v_fmac_f32_e32 v59, 0x3e000000, v40
	v_fmac_f32_e32 v61, 0x3e000000, v41
	v_mfma_f32_16x16x32_bf16 v[38:41], v[130:133], v[6:9], 0
	v_cndmask_b32_e64 v55, v194, v55, s[44:45]
	v_cndmask_b32_e64 v103, v194, v57, s[48:49]
	v_max3_f32 v42, v46, v55, v103
	v_cndmask_b32_e64 v104, v194, v59, s[50:51]
	v_cndmask_b32_e64 v105, v194, v61, s[52:53]
	v_max3_f32 v46, v42, v104, v105
	ds_read2_b32 v[42:43], v176 offset0:147 offset1:178
	ds_read2_b32 v[44:45], v177 offset0:147 offset1:178
	v_mfma_f32_16x16x32_bf16 v[34:37], v[34:37], v[2:5], v[38:41]
	s_waitcnt lgkmcnt(1)
	v_fmac_f32_e32 v43, 0x3e000000, v18
	s_nop 0
	ds_read2_b32 v[38:39], v197 offset0:147 offset1:178
	s_waitcnt vmcnt(1)
	v_mfma_f32_16x16x32_bf16 v[6:9], v[14:17], v[6:9], 0
	s_nop 1
	v_fmamk_f32 v34, v34, 0x3e000000, v42
	v_cndmask_b32_e32 v42, v194, v34, vcc
	s_waitcnt lgkmcnt(1)
	v_fmamk_f32 v40, v35, 0x3e000000, v44
	ds_read2_b32 v[34:35], v198 offset0:147 offset1:178
	v_cndmask_b32_e64 v44, v194, v40, s[40:41]
	s_waitcnt lgkmcnt(1)
	v_fmamk_f32 v36, v36, 0x3e000000, v38
	v_max3_f32 v40, v46, v42, v44
	v_cndmask_b32_e64 v38, v194, v36, s[46:47]
	s_waitcnt lgkmcnt(0)
	v_fmamk_f32 v34, v37, 0x3e000000, v34
	v_cndmask_b32_e64 v34, v194, v34, s[42:43]
	v_max3_f32 v46, v40, v38, v34
	ds_read2_b32 v[36:37], v199 offset0:147 offset1:178
	ds_read2_b32 v[40:41], v200 offset0:147 offset1:178
	ds_read2_b32 v[30:31], v201 offset0:147 offset1:178
	s_waitcnt vmcnt(0)
	v_mfma_f32_16x16x32_bf16 v[2:5], v[10:13], v[2:5], v[6:9]
	v_fmac_f32_e32 v45, 0x3e000000, v19
	s_waitcnt lgkmcnt(2)
	v_fmamk_f32 v26, v26, 0x3e000000, v36
	v_cndmask_b32_e64 v36, v194, v26, s[44:45]
	s_waitcnt lgkmcnt(1)
	v_fmamk_f32 v26, v27, 0x3e000000, v40
	v_cndmask_b32_e64 v40, v194, v26, s[48:49]
	ds_read2_b32 v[26:27], v202 offset0:147 offset1:178
	s_waitcnt lgkmcnt(1)
	v_fmamk_f32 v28, v28, 0x3e000000, v30
	v_max3_f32 v32, v46, v36, v40
	v_cndmask_b32_e64 v106, v194, v28, s[50:51]
	v_cndmask_b32_e32 v43, v194, v43, vcc
	s_waitcnt lgkmcnt(0)
	v_fmamk_f32 v26, v29, 0x3e000000, v26
	v_cndmask_b32_e64 v107, v194, v26, s[52:53]
	v_max3_f32 v26, v32, v106, v107
	v_cndmask_b32_e64 v45, v194, v45, s[40:41]
	v_fmac_f32_e32 v39, 0x3e000000, v20
	v_fmac_f32_e32 v35, 0x3e000000, v21
	v_fmac_f32_e32 v31, 0x3e000000, v4
	v_and_b32_e32 v4, 64, v178
	v_max3_f32 v18, v26, v43, v45
	v_cndmask_b32_e64 v39, v194, v39, s[46:47]
	v_cndmask_b32_e64 v108, v194, v35, s[42:43]
	v_fmac_f32_e32 v37, 0x3e000000, v2
	v_fmac_f32_e32 v41, 0x3e000000, v3
	v_xor_b32_e32 v3, 16, v178
	v_add_u32_e32 v4, 64, v4
	v_max3_f32 v14, v18, v39, v108
	v_cndmask_b32_e64 v109, v194, v37, s[44:45]
	v_cndmask_b32_e64 v41, v194, v41, s[48:49]
	v_fmac_f32_e32 v27, 0x3e000000, v5
	v_cmp_lt_i32_e32 vcc, v3, v4
	v_max3_f32 v2, v14, v109, v41
	v_cndmask_b32_e64 v110, v194, v31, s[50:51]
	v_cndmask_b32_e64 v111, v194, v27, s[52:53]
	v_cndmask_b32_e32 v3, v178, v3, vcc
	v_max3_f32 v2, v2, v110, v111
	v_lshlrev_b32_e32 v112, 2, v3
	ds_bpermute_b32 v3, v112, v2
	s_waitcnt lgkmcnt(0)
	v_max_f32_e32 v3, v3, v3
	v_max_f32_e32 v2, v2, v3
	v_xor_b32_e32 v3, 32, v178
	v_cmp_lt_i32_e32 vcc, v3, v4
	s_nop 1
	v_cndmask_b32_e32 v3, v178, v3, vcc
	v_lshlrev_b32_e32 v113, 2, v3
	ds_bpermute_b32 v3, v113, v2
	s_waitcnt lgkmcnt(0)
; __device__ __forceinline__ unsigned pk2(float lo, float hi) { return f2bf(lo) | (f2bf(hi) << 16); }
; __device__ __forceinline__ void na2_task(const Params& p_, int l, int task, unsigned char* lds) {
;     ...
;     float sum = 0.f; unsigned pp[16][2];
; #pragma unroll
;     for (int kt = 0; kt < 16; ++kt) { const float e0 = __expf(sc[kt][0] - mx), e1 = __expf(sc[kt][1] - mx), e2 = __expf(sc[kt][2] - mx), e3 = __expf(sc[kt][3] - mx);
;         sum += (e0 + e1) + (e2 + e3); pp[kt][0] = pk2(e0, e1); pp[kt][1] = pk2(e2, e3); }
	v_max_f32_e32 v3, v3, v3
	v_max_f32_e32 v114, v2, v3
	v_sub_f32_e32 v6, v84, v114
	v_mul_f32_e32 v6, 0x3fb8aa3b, v6
	v_sub_f32_e32 v3, v68, v114
	v_exp_f32_e32 v60, v6
	v_sub_f32_e32 v6, v85, v114
	v_mul_f32_e32 v3, 0x3fb8aa3b, v3
	v_mul_f32_e32 v6, 0x3fb8aa3b, v6
	v_sub_f32_e32 v2, v66, v114
	v_exp_f32_e32 v4, v3
	v_sub_f32_e32 v3, v70, v114
	v_sub_f32_e32 v5, v72, v114
	v_exp_f32_e32 v64, v6
	v_sub_f32_e32 v6, v83, v114
	v_mul_f32_e32 v2, 0x3fb8aa3b, v2
	v_mul_f32_e32 v3, 0x3fb8aa3b, v3
	v_mul_f32_e32 v5, 0x3fb8aa3b, v5
	v_mul_f32_e32 v6, 0x3fb8aa3b, v6
	v_exp_f32_e32 v2, v2
	v_exp_f32_e32 v3, v3
	v_exp_f32_e32 v5, v5
	v_exp_f32_e32 v61, v6
	v_sub_f32_e32 v6, v82, v114
	v_mul_f32_e32 v6, 0x3fb8aa3b, v6
	v_exp_f32_e32 v65, v6
	v_pk_add_f32 v[6:7], v[2:3], v[4:5]
	v_sub_f32_e32 v8, v87, v114
	v_add_f32_e32 v6, v6, v7
	v_add_f32_e32 v9, 0, v6
	v_pk_add_f32 v[6:7], v[60:61], v[64:65]
	v_mul_f32_e32 v8, 0x3fb8aa3b, v8
	v_pk_add_f32 v[6:7], v[6:7], v[6:7] op_sel_hi:[0,1]
	v_sub_f32_e32 v6, v62, v114
	v_mul_f32_e32 v6, 0x3fb8aa3b, v6
	v_exp_f32_e32 v84, v6
	v_sub_f32_e32 v6, v63, v114
	v_mul_f32_e32 v6, 0x3fb8aa3b, v6
	v_exp_f32_e32 v85, v6
	v_sub_f32_e32 v6, v67, v114
	v_mul_f32_e32 v6, 0x3fb8aa3b, v6
	v_exp_f32_e32 v115, v6
	v_sub_f32_e32 v6, v69, v114
	v_mul_f32_e32 v6, 0x3fb8aa3b, v6
	v_exp_f32_e32 v116, v6
	v_sub_f32_e32 v6, v71, v114
	v_mul_f32_e32 v6, 0x3fb8aa3b, v6
	v_exp_f32_e32 v12, v6
	v_sub_f32_e32 v6, v73, v114
	v_mul_f32_e32 v6, 0x3fb8aa3b, v6
	v_exp_f32_e32 v62, v6
	v_sub_f32_e32 v6, v86, v114
	v_mul_f32_e32 v6, 0x3fb8aa3b, v6
	v_exp_f32_e32 v6, v6
	v_exp_f32_e32 v8, v8
	v_add_f32_e32 v13, v84, v85
	v_add_f32_e32 v63, v115, v116
	v_pk_add_f32 v[10:11], v[12:13], v[62:63]
	v_pk_add_f32 v[14:15], v[6:7], v[8:9]
	v_sub_f32_e32 v7, v88, v114
	v_pk_add_f32 v[10:11], v[10:11], v[14:15]
	v_mul_f32_e32 v7, 0x3fb8aa3b, v7
	v_pk_add_f32 v[14:15], v[10:11], v[10:11] op_sel_hi:[0,1]
	v_exp_f32_e32 v10, v7
	v_sub_f32_e32 v7, v89, v114
	v_mul_f32_e32 v7, 0x3fb8aa3b, v7
	v_exp_f32_e32 v58, v7
	v_sub_f32_e32 v7, v91, v114
	v_mul_f32_e32 v7, 0x3fb8aa3b, v7
	v_exp_f32_e32 v11, v7
	v_sub_f32_e32 v7, v92, v114
	v_mul_f32_e32 v7, 0x3fb8aa3b, v7
	v_exp_f32_e32 v59, v7
	v_sub_f32_e32 v7, v93, v114
	v_mul_f32_e32 v7, 0x3fb8aa3b, v7
	v_exp_f32_e32 v13, v7
	v_sub_f32_e32 v7, v94, v114
	v_mul_f32_e32 v7, 0x3fb8aa3b, v7
	v_exp_f32_e32 v86, v7
	v_sub_f32_e32 v7, v95, v114
	v_mul_f32_e32 v7, 0x3fb8aa3b, v7
	v_exp_f32_e32 v87, v7
	v_sub_f32_e32 v7, v96, v114
	v_mul_f32_e32 v7, 0x3fb8aa3b, v7
	v_exp_f32_e32 v88, v7
	v_sub_f32_e32 v7, v97, v114
	v_pk_add_f32 v[16:17], v[10:11], v[58:59]
	v_mul_f32_e32 v7, 0x3fb8aa3b, v7
	v_pk_add_f32 v[18:19], v[16:17], v[16:17] op_sel_hi:[0,1]
	v_exp_f32_e32 v16, v7
	v_sub_f32_e32 v7, v134, v114
	v_mul_f32_e32 v7, 0x3fb8aa3b, v7
	v_exp_f32_e32 v20, v7
	v_sub_f32_e32 v7, v135, v114
	v_mul_f32_e32 v7, 0x3fb8aa3b, v7
	v_exp_f32_e32 v18, v7
	v_sub_f32_e32 v7, v136, v114
	v_mul_f32_e32 v7, 0x3fb8aa3b, v7
	v_exp_f32_e32 v14, v7
	v_sub_f32_e32 v7, v137, v114
	v_mul_f32_e32 v7, 0x3fb8aa3b, v7
	v_exp_f32_e32 v68, v7
	v_sub_f32_e32 v7, v138, v114
	v_mul_f32_e32 v7, 0x3fb8aa3b, v7
	v_exp_f32_e32 v72, v7
	v_sub_f32_e32 v7, v139, v114
	v_mul_f32_e32 v7, 0x3fb8aa3b, v7
	v_exp_f32_e32 v69, v7
	v_sub_f32_e32 v7, v140, v114
	v_mul_f32_e32 v7, 0x3fb8aa3b, v7
	v_exp_f32_e32 v73, v7
	v_sub_f32_e32 v7, v98, v114
	v_mul_f32_e32 v7, 0x3fb8aa3b, v7
	v_pk_add_f32 v[24:25], v[18:19], v[14:15]
	v_exp_f32_e32 v19, v7
	v_sub_f32_e32 v7, v48, v114
	v_add_f32_e32 v17, v13, v86
	v_add_f32_e32 v21, v87, v88
	v_mul_f32_e32 v7, 0x3fb8aa3b, v7
	v_pk_add_f32 v[22:23], v[16:17], v[20:21]
	v_exp_f32_e32 v21, v7
	v_sub_f32_e32 v7, v50, v114
	v_mul_f32_e32 v7, 0x3fb8aa3b, v7
	v_exp_f32_e32 v89, v7
	v_sub_f32_e32 v7, v52, v114
	v_mul_f32_e32 v7, 0x3fb8aa3b, v7
	v_exp_f32_e32 v91, v7
	v_sub_f32_e32 v7, v54, v114
	v_mul_f32_e32 v7, 0x3fb8aa3b, v7
	v_exp_f32_e32 v66, v7
	v_sub_f32_e32 v7, v99, v114
	v_pk_add_f32 v[22:23], v[22:23], v[24:25]
	v_mul_f32_e32 v7, 0x3fb8aa3b, v7
	v_pk_add_f32 v[56:57], v[22:23], v[22:23] op_sel_hi:[0,1]
	v_pk_add_f32 v[22:23], v[68:69], v[72:73]
	v_exp_f32_e32 v70, v7
	v_sub_f32_e32 v7, v100, v114
	v_pk_add_f32 v[46:47], v[22:23], v[22:23] op_sel_hi:[0,1]
	v_mul_f32_e32 v7, 0x3fb8aa3b, v7
	v_exp_f32_e32 v46, v7
	v_sub_f32_e32 v7, v101, v114
	v_mul_f32_e32 v7, 0x3fb8aa3b, v7
	v_exp_f32_e32 v56, v7
	v_add_f32_e32 v67, v19, v21
	v_add_f32_e32 v71, v89, v91
	v_pk_add_f32 v[22:23], v[66:67], v[70:71]
	v_pk_add_f32 v[24:25], v[46:47], v[56:57]
	v_sub_f32_e32 v7, v102, v114
	v_pk_add_f32 v[22:23], v[22:23], v[24:25]
	v_mul_f32_e32 v7, 0x3fb8aa3b, v7
	v_pk_add_f32 v[26:27], v[22:23], v[22:23] op_sel_hi:[0,1]
	v_exp_f32_e32 v22, v7
	v_sub_f32_e32 v7, v49, v114
	v_mul_f32_e32 v7, 0x3fb8aa3b, v7
	v_exp_f32_e32 v24, v7
	v_sub_f32_e32 v7, v51, v114
	v_mul_f32_e32 v7, 0x3fb8aa3b, v7
	v_exp_f32_e32 v23, v7
	v_sub_f32_e32 v7, v53, v114
	v_mul_f32_e32 v7, 0x3fb8aa3b, v7
	v_exp_f32_e32 v25, v7
	v_sub_f32_e32 v7, v55, v114
	v_mul_f32_e32 v7, 0x3fb8aa3b, v7
	v_exp_f32_e32 v67, v7
	v_sub_f32_e32 v7, v103, v114
	v_mul_f32_e32 v7, 0x3fb8aa3b, v7
	v_exp_f32_e32 v71, v7
	v_sub_f32_e32 v7, v104, v114
	v_mul_f32_e32 v7, 0x3fb8aa3b, v7
	v_exp_f32_e32 v92, v7
	v_sub_f32_e32 v7, v105, v114
	v_mul_f32_e32 v7, 0x3fb8aa3b, v7
	v_exp_f32_e32 v93, v7
	v_sub_f32_e32 v7, v42, v114
	v_pk_add_f32 v[28:29], v[22:23], v[24:25]
	v_mul_f32_e32 v7, 0x3fb8aa3b, v7
	v_pk_add_f32 v[30:31], v[28:29], v[28:29] op_sel_hi:[0,1]
	v_exp_f32_e32 v28, v7
	v_sub_f32_e32 v7, v44, v114
	v_mul_f32_e32 v7, 0x3fb8aa3b, v7
	v_exp_f32_e32 v32, v7
	v_sub_f32_e32 v7, v38, v114
	v_mul_f32_e32 v7, 0x3fb8aa3b, v7
; __device__ __forceinline__ unsigned pk2(float lo, float hi) { return f2bf(lo) | (f2bf(hi) << 16); }
; #define MFMA16(a, b, c) __builtin_amdgcn_mfma_f32_16x16x32_bf16(a, b, c, 0, 0, 0)
; __device__ __forceinline__ void na2_task(const Params& p_, int l, int task, unsigned char* lds) {
;     ...
;     float sum = 0.f; unsigned pp[16][2];
; #pragma unroll
;     for (int kt = 0; kt < 16; ++kt) { const float e0 = __expf(sc[kt][0] - mx), e1 = __expf(sc[kt][1] - mx), e2 = __expf(sc[kt][2] - mx), e3 = __expf(sc[kt][3] - mx);
;         sum += (e0 + e1) + (e2 + e3); pp[kt][0] = pk2(e0, e1); pp[kt][1] = pk2(e2, e3); }
;     sum += __shfl_xor(sum, 16); sum += __shfl_xor(sum, 32);
;     const float inv = 1.f / sum;
;     const bf16* VTh = VT + (size_t)hh * 64 * 520;
; #pragma unroll
;     for (int dt = 0; dt < 4; ++dt) { f32x4 o = {0.f, 0.f, 0.f, 0.f};
; #pragma unroll
;         for (int t = 0; t < 8; ++t) { const int k0 = 2 * t, k1 = 2 * t + 1, a0 = k0 / 2, c0 = k0 % 2, a1 = k1 / 2, c1 = k1 % 2;
;             const u32x2 vlo = *(const u32x2*)(VTh + (16 * dt + fr) * 520 + a0 * 64 + kst + 16 * c0 + 4 * fq), vhi = *(const u32x2*)(VTh + (16 * dt + fr) * 520 + a1 * 64 + kst + 16 * c1 + 4 * fq);
;             o = MFMA16(mk8(vlo.x, vlo.y, vhi.x, vhi.y), mk8(pp[k0][0], pp[k0][1], pp[k1][0], pp[k1][1]), o); }
	v_exp_f32_e32 v30, v7
	v_sub_f32_e32 v7, v34, v114
	v_mul_f32_e32 v7, 0x3fb8aa3b, v7
	v_exp_f32_e32 v26, v7
	v_sub_f32_e32 v7, v36, v114
	v_mul_f32_e32 v7, 0x3fb8aa3b, v7
	v_exp_f32_e32 v48, v7
	v_sub_f32_e32 v7, v40, v114
	v_mul_f32_e32 v7, 0x3fb8aa3b, v7
	v_exp_f32_e32 v52, v7
	v_sub_f32_e32 v7, v106, v114
	v_mul_f32_e32 v7, 0x3fb8aa3b, v7
	v_exp_f32_e32 v49, v7
	v_sub_f32_e32 v7, v107, v114
	v_mul_f32_e32 v7, 0x3fb8aa3b, v7
	v_exp_f32_e32 v53, v7
	v_sub_f32_e32 v7, v43, v114
	v_mul_f32_e32 v7, 0x3fb8aa3b, v7
	v_pk_add_f32 v[36:37], v[30:31], v[26:27]
	v_exp_f32_e32 v31, v7
	v_sub_f32_e32 v7, v45, v114
	v_add_f32_e32 v29, v67, v71
	v_add_f32_e32 v33, v92, v93
	v_mul_f32_e32 v7, 0x3fb8aa3b, v7
	v_pk_add_f32 v[34:35], v[28:29], v[32:33]
	v_exp_f32_e32 v33, v7
	v_sub_f32_e32 v7, v39, v114
	v_mul_f32_e32 v7, 0x3fb8aa3b, v7
	v_exp_f32_e32 v94, v7
	v_sub_f32_e32 v7, v108, v114
	v_mul_f32_e32 v7, 0x3fb8aa3b, v7
	v_exp_f32_e32 v95, v7
	v_sub_f32_e32 v7, v109, v114
	v_mul_f32_e32 v7, 0x3fb8aa3b, v7
	v_exp_f32_e32 v50, v7
	v_sub_f32_e32 v7, v41, v114
	v_pk_add_f32 v[34:35], v[34:35], v[36:37]
	v_mul_f32_e32 v7, 0x3fb8aa3b, v7
	v_pk_add_f32 v[36:37], v[34:35], v[34:35] op_sel_hi:[0,1]
	v_pk_add_f32 v[34:35], v[48:49], v[52:53]
	v_exp_f32_e32 v54, v7
	v_sub_f32_e32 v7, v110, v114
	v_pk_add_f32 v[34:35], v[34:35], v[34:35] op_sel_hi:[0,1]
	v_mul_f32_e32 v7, 0x3fb8aa3b, v7
	v_exp_f32_e32 v34, v7
	v_sub_f32_e32 v7, v111, v114
	v_mul_f32_e32 v7, 0x3fb8aa3b, v7
	v_exp_f32_e32 v36, v7
	v_add_f32_e32 v51, v31, v33
	v_add_f32_e32 v55, v94, v95
	v_pk_add_f32 v[38:39], v[50:51], v[54:55]
	v_pk_add_f32 v[40:41], v[34:35], v[36:37]
	s_nop 0
	v_pk_add_f32 v[38:39], v[38:39], v[40:41]
	s_nop 0
	v_add_f32_e32 v7, v38, v39
	ds_bpermute_b32 v9, v112, v7
	v_lshlrev_b64 v[38:39], 12, v[74:75]
	v_lshl_add_u64 v[38:39], s[62:63], 0, v[38:39]
	v_lshl_add_u64 v[38:39], v[38:39], 0, v[76:77]
	v_lshl_add_u64 v[42:43], v[38:39], 0, v[0:1]
	s_waitcnt lgkmcnt(0)
	v_add_f32_e32 v7, v7, v9
	ds_bpermute_b32 v9, v113, v7
	s_nop 0
	s_nop 0
	s_nop 0
	s_nop 0
	s_waitcnt lgkmcnt(0)
	v_add_f32_e32 v7, v7, v9
	v_div_scale_f32 v9, s[12:13], v7, v7, 1.0
	v_rcp_f32_e32 v15, v9
	s_nop 0
	s_nop 0
	s_mov_b64 s[12:13], 0x1400
	v_fma_f32 v17, -v9, v15, 1.0
	v_fmac_f32_e32 v15, v17, v15
	v_div_scale_f32 v17, vcc, 1.0, v7, 1.0
	v_mul_f32_e32 v27, v17, v15
	v_fma_f32 v29, -v9, v27, v17
	v_fmac_f32_e32 v27, v29, v15
	v_fma_f32 v9, -v9, v27, v17
	v_div_fmas_f32 v9, v9, v15, v27
	v_div_fixup_f32 v40, v9, v7, 1.0
	v_lshl_add_u32 v7, v80, 1, v81
	v_mul_u32_u24_e32 v9, 0x410, v90
	v_add3_u32 v0, v7, v9, v0
	s_nop 0
	s_nop 0
	v_bfe_u32 v15, v5, 16, 1
	v_bfe_u32 v17, v4, 16, 1
	v_cvt_pk_bf16_f32 v207, v60, v64
	v_cvt_pk_bf16_f32 v206, v61, v65
	v_add3_u32 v17, v4, v17, s14
	v_add3_u32 v15, v5, v15, s14
	s_nop 0
	s_nop 0
	v_bfe_u32 v7, v2, 16, 1
	v_bfe_u32 v9, v3, 16, 1
	s_nop 0
	s_nop 0
	v_add3_u32 v3, v3, v9, s14
	v_add3_u32 v2, v2, v7, s14
	s_nop 0
	s_nop 0
	v_mov_b32_e32 v5, v206
	v_mov_b32_e32 v4, v207
	v_bfe_u32 v7, v8, 16, 1
	v_cvt_pk_bf16_f32 v208, v12, v62
	v_lshrrev_b32_e32 v3, 16, v3
	v_add3_u32 v7, v8, v7, s14
	s_nop 0
	v_bfe_u32 v9, v6, 16, 1
	s_nop 0
	v_and_or_b32 v3, v15, s15, v3
	v_cvt_pk_bf16_f32 v209, v115, v116
	v_add3_u32 v6, v6, v9, s14
	s_nop 0
	s_nop 0
	s_nop 0
	v_lshrrev_b32_e32 v6, 16, v6
	s_nop 0
	s_nop 0
	v_and_or_b32 v9, v7, s15, v6
	v_mov_b32_e32 v8, v208
	v_mov_b32_e32 v7, v209
	v_cvt_pk_bf16_f32 v210, v87, v88
	v_cvt_pk_bf16_f32 v211, v13, v86
	s_nop 0
	s_nop 0
	s_nop 0
	s_nop 0
	s_nop 0
	s_nop 0
	v_mov_b32_e32 v13, v210
	v_mov_b32_e32 v12, v211
	s_nop 0
	s_nop 0
	s_nop 0
	s_nop 0
	v_cvt_pk_bf16_f32 v212, v18, v14
	v_cvt_pk_bf16_f32 v213, v16, v20
	s_nop 0
	s_nop 0
	s_nop 0
	s_nop 0
	v_mov_b32_e32 v15, v212
	v_mov_b32_e32 v14, v213
	v_bfe_u32 v29, v21, 16, 1
	v_add3_u32 v29, v21, v29, s14
	v_bfe_u32 v21, v46, 16, 1
	v_add3_u32 v21, v46, v21, s14
	v_add_co_u32_e32 v46, vcc, s74, v78
	ds_read2_b64 v[74:77], v0 offset1:4
	s_nop 0
	v_addc_co_u32_e32 v47, vcc, 0, v79, vcc
	global_load_dwordx2 v[46:47], v[46:47], off offset:1024
	ds_read2_b64 v[80:83], v0 offset0:16 offset1:20
	v_lshrrev_b32_e32 v2, 16, v2
	v_and_or_b32 v2, v17, s15, v2
	s_nop 0
	v_cvt_pk_bf16_f32 v214, v84, v85
	s_waitcnt lgkmcnt(1)
	v_mfma_f32_16x16x32_bf16 v[74:77], v[74:77], v[2:5], 0
	s_nop 0
	s_nop 0
	s_nop 0
	v_mov_b32_e32 v6, v214
	s_nop 0
	v_cvt_pk_bf16_f32 v215, v11, v59
	s_waitcnt lgkmcnt(0)
	v_mfma_f32_16x16x32_bf16 v[60:63], v[80:83], v[6:9], v[74:77]
	v_cvt_pk_bf16_f32 v216, v10, v58
	s_nop 0
	s_nop 0
	ds_read2_b64 v[74:77], v0 offset0:32 offset1:36
	s_nop 0
	s_nop 0
	s_nop 0
	v_mov_b32_e32 v11, v215
	v_mov_b32_e32 v10, v216
	s_nop 0
	v_cvt_pk_bf16_f32 v217, v69, v73
	s_waitcnt lgkmcnt(0)
	v_mfma_f32_16x16x32_bf16 v[58:61], v[74:77], v[10:13], v[60:63]
	v_cvt_pk_bf16_f32 v218, v68, v72
	s_nop 0
	s_nop 0
	ds_read2_b64 v[62:65], v0 offset0:48 offset1:52
	s_nop 0
	s_nop 0
	s_nop 0
	s_nop 0
	s_nop 0
	v_mov_b32_e32 v17, v217
	v_mov_b32_e32 v16, v218
	v_bfe_u32 v35, v19, 16, 1
	s_nop 0
	s_waitcnt lgkmcnt(0)
	v_mfma_f32_16x16x32_bf16 v[58:61], v[62:65], v[14:17], v[58:61]
	ds_read2_b64 v[62:65], v0 offset0:64 offset1:68
	s_nop 0
	v_bfe_u32 v18, v56, 16, 1
	v_cvt_pk_bf16_f32 v219, v66, v70
	v_cvt_pk_bf16_f32 v220, v89, v91
	s_nop 0
	s_nop 0
	v_add3_u32 v19, v19, v35, s14
	v_add3_u32 v18, v56, v18, s14
	s_nop 0
	s_nop 0
	v_lshrrev_b32_e32 v21, 16, v21
	v_lshrrev_b32_e32 v35, 16, v19
	s_nop 0
	s_nop 0
	v_and_or_b32 v21, v18, s15, v21
	v_mov_b32_e32 v20, v219
	v_mov_b32_e32 v19, v220
	v_and_or_b32 v18, v29, s15, v35
	v_cvt_pk_bf16_f32 v221, v92, v93
	s_nop 0
	s_waitcnt lgkmcnt(0)
; __device__ __forceinline__ unsigned pk2(float lo, float hi) { return f2bf(lo) | (f2bf(hi) << 16); }
; __device__ __forceinline__ float bflo(unsigned u) { return __uint_as_float(u << 16); }
; __device__ __forceinline__ float bfhi(unsigned u) { return __uint_as_float(u & 0xffff0000u); }
; __device__ __forceinline__ float silu_f(float v) { return v / (1.f + __expf(-v)); }
; #define MFMA16(a, b, c) __builtin_amdgcn_mfma_f32_16x16x32_bf16(a, b, c, 0, 0, 0)
; __device__ __forceinline__ void na2_task(const Params& p_, int l, int task, unsigned char* lds) {
;     ...
;     for (int dt = 0; dt < 4; ++dt) { f32x4 o = {0.f, 0.f, 0.f, 0.f};
; #pragma unroll
;         for (int t = 0; t < 8; ++t) { const int k0 = 2 * t, k1 = 2 * t + 1, a0 = k0 / 2, c0 = k0 % 2, a1 = k1 / 2, c1 = k1 % 2;
;             const u32x2 vlo = *(const u32x2*)(VTh + (16 * dt + fr) * 520 + a0 * 64 + kst + 16 * c0 + 4 * fq), vhi = *(const u32x2*)(VTh + (16 * dt + fr) * 520 + a1 * 64 + kst + 16 * c1 + 4 * fq);
;             o = MFMA16(mk8(vlo.x, vlo.y, vhi.x, vhi.y), mk8(pp[k0][0], pp[k0][1], pp[k1][0], pp[k1][1]), o); }
;         const u32x2 gz = *(const u32x2*)(Z + qtok * DIN + 5 * DG + h * 64 + 16 * dt + 4 * fq); u32x2 ov;
;         ov.x = pk2(o[0] * inv * silu_f(bflo(gz.x)), o[1] * inv * silu_f(bfhi(gz.x))); ov.y = pk2(o[2] * inv * silu_f(bflo(gz.y)), o[3] * inv * silu_f(bfhi(gz.y)));
;         *(u32x2*)(CAT + qtok * DM + 512 + h * 64 + 16 * dt + 4 * fq) = ov; }
	v_mfma_f32_16x16x32_bf16 v[56:59], v[62:65], v[18:21], v[58:61]
	v_bfe_u32 v35, v25, 16, 1
	v_bfe_u32 v37, v24, 16, 1
	v_add3_u32 v37, v24, v37, s14
	ds_read2_b64 v[60:63], v0 offset0:80 offset1:84
	v_add3_u32 v35, v25, v35, s14
	s_nop 0
	s_nop 0
	v_bfe_u32 v27, v22, 16, 1
	v_bfe_u32 v29, v23, 16, 1
	v_cvt_pk_bf16_f32 v222, v67, v71
	s_nop 0
	v_add3_u32 v23, v23, v29, s14
	v_add3_u32 v22, v22, v27, s14
	v_lshrrev_b32_e32 v22, 16, v22
	v_lshrrev_b32_e32 v23, 16, v23
	s_nop 0
	s_nop 0
	v_mov_b32_e32 v25, v221
	v_mov_b32_e32 v24, v222
	v_and_or_b32 v23, v35, s15, v23
	v_and_or_b32 v22, v37, s15, v22
	s_nop 0
	s_nop 0
	s_waitcnt lgkmcnt(0)
	v_mfma_f32_16x16x32_bf16 v[56:59], v[60:63], v[22:25], v[56:59]
	ds_read2_b64 v[60:63], v0 offset0:96 offset1:100
	s_nop 0
	s_nop 0
	v_cvt_pk_bf16_f32 v223, v30, v26
	v_cvt_pk_bf16_f32 v226, v28, v32
	s_nop 0
	s_nop 0
	v_cvt_pk_bf16_f32 v224, v49, v53
	v_cvt_pk_bf16_f32 v225, v48, v52
	s_nop 0
	s_nop 0
	s_nop 0
	s_nop 0
	s_nop 0
	s_nop 0
	s_nop 0
	s_nop 0
	s_nop 0
	s_nop 0
	v_mov_b32_e32 v27, v223
	v_mov_b32_e32 v29, v224
	v_mov_b32_e32 v28, v225
	v_mov_b32_e32 v26, v226
	v_bfe_u32 v30, v36, 16, 1
	v_bfe_u32 v37, v33, 16, 1
	s_waitcnt lgkmcnt(0)
	v_mfma_f32_16x16x32_bf16 v[56:59], v[60:63], v[26:29], v[56:59]
	ds_read2_b64 v[60:63], v0 offset0:112 offset1:116
	v_add3_u32 v30, v36, v30, s14
	v_add3_u32 v36, v33, v37, s14
	v_bfe_u32 v33, v34, 16, 1
	v_bfe_u32 v37, v31, 16, 1
	s_nop 0
	s_nop 0
	v_cvt_pk_bf16_f32 v227, v50, v54
	v_cvt_pk_bf16_f32 v228, v94, v95
	v_add3_u32 v33, v34, v33, s14
	s_nop 0
	s_nop 0
	v_add3_u32 v31, v31, v37, s14
	s_nop 0
	s_nop 0
	v_lshrrev_b32_e32 v33, 16, v33
	v_lshrrev_b32_e32 v37, 16, v31
	s_nop 0
	s_nop 0
	v_and_or_b32 v33, v30, s15, v33
	v_mov_b32_e32 v32, v227
	v_mov_b32_e32 v31, v228
	v_and_or_b32 v30, v36, s15, v37
	s_waitcnt vmcnt(0)
	v_lshlrev_b32_e32 v41, 16, v47
	v_lshl_add_u64 v[44:45], v[78:79], 0, s[12:13]
	s_waitcnt lgkmcnt(0)
	v_mfma_f32_16x16x32_bf16 v[34:37], v[60:63], v[30:33], v[56:59]
	global_load_dwordx2 v[48:49], v[44:45], off offset:32
	global_load_dwordx2 v[50:51], v[44:45], off offset:64
	s_nop 0
	global_load_dwordx2 v[44:45], v[44:45], off offset:96
	v_lshlrev_b32_e32 v56, 16, v46
	v_mul_f32_e32 v52, 0xbfb8aa3b, v56
	v_and_b32_e32 v57, 0xffff0000, v47
	v_mul_f32_e32 v47, 0xbfb8aa3b, v41
	v_exp_f32_e32 v52, v52
	v_exp_f32_e32 v53, v47
	s_mov_b64 s[12:13], 0x12d20400
	v_lshl_add_u64 v[38:39], v[42:43], 0, s[12:13]
	v_mov_b32_e32 v54, v34
	v_pk_add_f32 v[52:53], v[52:53], 1.0 op_sel_hi:[1,0]
	v_mov_b32_e32 v55, v36
	v_div_scale_f32 v47, s[12:13], v53, v53, v41
	v_rcp_f32_e32 v59, v47
	v_and_b32_e32 v58, 0xffff0000, v46
	v_pk_mul_f32 v[54:55], v[40:41], v[54:55] op_sel_hi:[0,1]
	v_mul_f32_e32 v46, 0xbfb8aa3b, v58
	v_fma_f32 v34, -v47, v59, 1.0
	v_fmac_f32_e32 v59, v34, v59
	v_div_scale_f32 v34, vcc, v41, v53, v41
	v_mul_f32_e32 v36, v34, v59
	v_fma_f32 v60, -v47, v36, v34
	v_fmac_f32_e32 v36, v60, v59
	v_fma_f32 v34, -v47, v36, v34
	v_div_scale_f32 v47, s[12:13], v52, v52, v56
	v_rcp_f32_e32 v60, v47
	v_div_fmas_f32 v34, v34, v59, v36
	v_div_fixup_f32 v53, v34, v53, v41
	v_exp_f32_e32 v46, v46
	v_fma_f32 v34, -v47, v60, 1.0
	v_fmac_f32_e32 v60, v34, v60
	v_div_scale_f32 v34, vcc, v56, v52, v56
	v_mul_f32_e32 v36, v34, v60
	v_fma_f32 v41, -v47, v36, v34
	v_fmac_f32_e32 v36, v41, v60
	v_mul_f32_e32 v41, 0xbfb8aa3b, v57
	v_fma_f32 v34, -v47, v36, v34
	v_exp_f32_e32 v47, v41
	v_div_fmas_f32 v34, v34, v60, v36
	v_div_fixup_f32 v52, v34, v52, v56
	v_mov_b32_e32 v36, v35
	v_pk_add_f32 v[46:47], v[46:47], 1.0 op_sel_hi:[1,0]
	v_pk_mul_f32 v[64:65], v[54:55], v[52:53]
	v_div_scale_f32 v34, s[12:13], v47, v47, v57
	v_rcp_f32_e32 v41, v34
	v_div_scale_f32 v52, s[12:13], v46, v46, v58
	v_rcp_f32_e32 v56, v52
	v_fma_f32 v35, -v34, v41, 1.0
	v_pk_mul_f32 v[60:61], v[40:41], v[36:37] op_sel_hi:[0,1]
	v_fmac_f32_e32 v41, v35, v41
	v_div_scale_f32 v35, vcc, v57, v47, v57
	v_mul_f32_e32 v36, v35, v41
	v_fma_f32 v37, -v34, v36, v35
	v_fmac_f32_e32 v36, v37, v41
	v_fma_f32 v34, -v34, v36, v35
	v_div_fmas_f32 v34, v34, v41, v36
	v_div_fixup_f32 v47, v34, v47, v57
	v_fma_f32 v34, -v52, v56, 1.0
	v_add_u32_e32 v66, 0x4000, v0
	v_fmac_f32_e32 v56, v34, v56
	v_div_scale_f32 v41, vcc, v58, v46, v58
	ds_read2_b64 v[34:37], v66 offset0:32 offset1:36
	v_mul_f32_e32 v57, v41, v56
	v_fma_f32 v53, -v52, v57, v41
	v_fmac_f32_e32 v57, v53, v56
	v_fma_f32 v41, -v52, v57, v41
	ds_read2_b64 v[52:55], v66 offset0:48 offset1:52
	v_div_fmas_f32 v41, v41, v56, v57
	v_div_fixup_f32 v46, v41, v46, v58
	ds_read2_b64 v[56:59], v66 offset0:64 offset1:68
	s_waitcnt lgkmcnt(2)
	v_mfma_f32_16x16x32_bf16 v[34:37], v[34:37], v[2:5], 0
	v_mul_f32_e64 v46, v60, v46
	v_mul_f32_e64 v47, v61, v47
	ds_read2_b64 v[60:63], v66 offset0:80 offset1:84
	v_and_b32_sdwa v41, v65, v179 dst_sel:DWORD dst_unused:UNUSED_PAD src0_sel:WORD_1 src1_sel:DWORD
	s_waitcnt lgkmcnt(2)
	v_mfma_f32_16x16x32_bf16 v[34:37], v[52:55], v[6:9], v[34:37]
	v_and_b32_sdwa v52, v64, v179 dst_sel:DWORD dst_unused:UNUSED_PAD src0_sel:WORD_1 src1_sel:DWORD
	v_add3_u32 v64, v64, v52, s14
	ds_read2_b64 v[52:55], v66 offset0:96 offset1:100
	s_waitcnt lgkmcnt(2)
	v_mfma_f32_16x16x32_bf16 v[34:37], v[56:59], v[10:13], v[34:37]
	ds_read2_b64 v[56:59], v66 offset0:112 offset1:116
	v_add3_u32 v41, v65, v41, s14
	v_and_b32_sdwa v65, v47, v179 dst_sel:DWORD dst_unused:UNUSED_PAD src0_sel:WORD_1 src1_sel:DWORD
	s_waitcnt lgkmcnt(2)
	v_mfma_f32_16x16x32_bf16 v[34:37], v[60:63], v[14:17], v[34:37]
	ds_read2_b64 v[60:63], v66 offset0:128 offset1:132
	v_and_b32_sdwa v67, v46, v179 dst_sel:DWORD dst_unused:UNUSED_PAD src0_sel:WORD_1 src1_sel:DWORD
	v_add3_u32 v47, v47, v65, s14
	s_waitcnt lgkmcnt(2)
; __device__ __forceinline__ unsigned pk2(float lo, float hi) { return f2bf(lo) | (f2bf(hi) << 16); }
; __device__ __forceinline__ float bflo(unsigned u) { return __uint_as_float(u << 16); }
; __device__ __forceinline__ float bfhi(unsigned u) { return __uint_as_float(u & 0xffff0000u); }
; __device__ __forceinline__ float silu_f(float v) { return v / (1.f + __expf(-v)); }
; #define MFMA16(a, b, c) __builtin_amdgcn_mfma_f32_16x16x32_bf16(a, b, c, 0, 0, 0)
; __device__ __forceinline__ void na2_task(const Params& p_, int l, int task, unsigned char* lds) {
;     ...
;     for (int dt = 0; dt < 4; ++dt) { f32x4 o = {0.f, 0.f, 0.f, 0.f};
; #pragma unroll
;         for (int t = 0; t < 8; ++t) { const int k0 = 2 * t, k1 = 2 * t + 1, a0 = k0 / 2, c0 = k0 % 2, a1 = k1 / 2, c1 = k1 % 2;
;             const u32x2 vlo = *(const u32x2*)(VTh + (16 * dt + fr) * 520 + a0 * 64 + kst + 16 * c0 + 4 * fq), vhi = *(const u32x2*)(VTh + (16 * dt + fr) * 520 + a1 * 64 + kst + 16 * c1 + 4 * fq);
;             o = MFMA16(mk8(vlo.x, vlo.y, vhi.x, vhi.y), mk8(pp[k0][0], pp[k0][1], pp[k1][0], pp[k1][1]), o); }
;         const u32x2 gz = *(const u32x2*)(Z + qtok * DIN + 5 * DG + h * 64 + 16 * dt + 4 * fq); u32x2 ov;
;         ov.x = pk2(o[0] * inv * silu_f(bflo(gz.x)), o[1] * inv * silu_f(bfhi(gz.x))); ov.y = pk2(o[2] * inv * silu_f(bflo(gz.y)), o[3] * inv * silu_f(bfhi(gz.y)));
;         *(u32x2*)(CAT + qtok * DM + 512 + h * 64 + 16 * dt + 4 * fq) = ov; }
	v_mfma_f32_16x16x32_bf16 v[34:37], v[52:55], v[18:21], v[34:37]
	ds_read2_b64 v[52:55], v66 offset0:144 offset1:148
	v_add3_u32 v46, v46, v67, s14
	v_and_b32_e32 v47, 0xffff0000, v47
	s_waitcnt lgkmcnt(2)
	v_mfma_f32_16x16x32_bf16 v[34:37], v[56:59], v[22:25], v[34:37]
	v_and_b32_e32 v46, 0xffff0000, v46
	v_add_co_u32_e32 v42, vcc, s9, v42
	s_waitcnt lgkmcnt(1)
	v_mfma_f32_16x16x32_bf16 v[34:37], v[60:63], v[26:29], v[34:37]
	v_or_b32_sdwa v47, v47, v41 dst_sel:DWORD dst_unused:UNUSED_PAD src0_sel:DWORD src1_sel:WORD_1
	v_or_b32_sdwa v46, v46, v64 dst_sel:DWORD dst_unused:UNUSED_PAD src0_sel:DWORD src1_sel:WORD_1
	v_addc_co_u32_e32 v43, vcc, 0, v43, vcc
	s_waitcnt lgkmcnt(0)
	v_mfma_f32_16x16x32_bf16 v[34:37], v[52:55], v[30:33], v[34:37]
	s_waitcnt vmcnt(2)
	v_lshlrev_b32_e32 v41, 16, v49
	v_lshlrev_b32_e32 v52, 16, v48
	global_store_dwordx2 v[42:43], v[46:47], off offset:1024
	v_mul_f32_e32 v42, 0xbfb8aa3b, v52
	v_mul_f32_e32 v43, 0xbfb8aa3b, v41
	v_exp_f32_e32 v42, v42
	v_exp_f32_e32 v43, v43
	v_and_b32_e32 v58, 0xffff0000, v48
	v_mov_b32_e32 v48, v34
	v_and_b32_e32 v53, 0xffff0000, v49
	v_pk_add_f32 v[42:43], v[42:43], 1.0 op_sel_hi:[1,0]
	v_mov_b32_e32 v49, v36
	v_div_scale_f32 v47, s[12:13], v43, v43, v41
	v_rcp_f32_e32 v54, v47
	v_pk_mul_f32 v[48:49], v[40:41], v[48:49] op_sel_hi:[0,1]
	v_mul_f32_e32 v46, 0xbfb8aa3b, v58
	v_exp_f32_e32 v46, v46
	v_fma_f32 v34, -v47, v54, 1.0
	v_fmac_f32_e32 v54, v34, v54
	v_div_scale_f32 v34, vcc, v41, v43, v41
	v_mul_f32_e32 v36, v34, v54
	v_fma_f32 v55, -v47, v36, v34
	v_fmac_f32_e32 v36, v55, v54
	v_fma_f32 v34, -v47, v36, v34
	v_div_scale_f32 v47, s[12:13], v42, v42, v52
	v_rcp_f32_e32 v55, v47
	v_div_fmas_f32 v34, v34, v54, v36
	v_div_fixup_f32 v43, v34, v43, v41
	v_add_u32_e32 v64, 0x8000, v0
	v_fma_f32 v34, -v47, v55, 1.0
	v_fmac_f32_e32 v55, v34, v55
	v_div_scale_f32 v34, vcc, v52, v42, v52
	v_mul_f32_e32 v36, v34, v55
	v_fma_f32 v41, -v47, v36, v34
	v_fmac_f32_e32 v36, v41, v55
	v_mul_f32_e32 v41, 0xbfb8aa3b, v53
	v_fma_f32 v34, -v47, v36, v34
	v_exp_f32_e32 v47, v41
	v_div_fmas_f32 v34, v34, v55, v36
	v_div_fixup_f32 v42, v34, v42, v52
	v_mov_b32_e32 v36, v35
	v_pk_add_f32 v[56:57], v[46:47], 1.0 op_sel_hi:[1,0]
	v_pk_mul_f32 v[42:43], v[48:49], v[42:43]
	v_div_scale_f32 v34, s[12:13], v57, v57, v53
	v_rcp_f32_e32 v41, v34
	v_div_scale_f32 v52, s[12:13], v56, v56, v58
	v_rcp_f32_e32 v59, v52
	v_fma_f32 v35, -v34, v41, 1.0
	v_pk_mul_f32 v[60:61], v[40:41], v[36:37] op_sel_hi:[0,1]
	v_fmac_f32_e32 v41, v35, v41
	v_div_scale_f32 v35, vcc, v53, v57, v53
	v_mul_f32_e32 v36, v35, v41
	v_fma_f32 v37, -v34, v36, v35
	v_fmac_f32_e32 v36, v37, v41
	v_fma_f32 v34, -v34, v36, v35
	v_div_fmas_f32 v34, v34, v41, v36
	v_div_fixup_f32 v63, v34, v57, v53
	ds_read2_b64 v[34:37], v64 offset0:64 offset1:68
	v_fma_f32 v41, -v52, v59, 1.0
	v_fmac_f32_e32 v59, v41, v59
	v_div_scale_f32 v41, vcc, v58, v56, v58
	ds_read2_b64 v[46:49], v64 offset0:80 offset1:84
	v_mul_f32_e32 v57, v41, v59
	v_fma_f32 v53, -v52, v57, v41
	v_fmac_f32_e32 v57, v53, v59
	v_fma_f32 v41, -v52, v57, v41
	ds_read2_b64 v[52:55], v64 offset0:96 offset1:100
	s_waitcnt lgkmcnt(2)
	v_mfma_f32_16x16x32_bf16 v[34:37], v[34:37], v[2:5], 0
	v_div_fmas_f32 v41, v41, v59, v57
	v_div_fixup_f32 v62, v41, v56, v58
	ds_read2_b64 v[56:59], v64 offset0:112 offset1:116
	s_waitcnt lgkmcnt(2)
	v_mfma_f32_16x16x32_bf16 v[34:37], v[46:49], v[6:9], v[34:37]
	ds_read2_b64 v[46:49], v64 offset0:128 offset1:132
	v_pk_mul_f32 v[60:61], v[60:61], v[62:63]
	v_and_b32_sdwa v41, v43, v179 dst_sel:DWORD dst_unused:UNUSED_PAD src0_sel:WORD_1 src1_sel:DWORD
	s_waitcnt lgkmcnt(2)
	v_mfma_f32_16x16x32_bf16 v[34:37], v[52:55], v[10:13], v[34:37]
	v_and_b32_sdwa v52, v42, v179 dst_sel:DWORD dst_unused:UNUSED_PAD src0_sel:WORD_1 src1_sel:DWORD
	v_add3_u32 v42, v42, v52, s14
	ds_read2_b64 v[52:55], v64 offset0:144 offset1:148
	s_waitcnt lgkmcnt(2)
	v_mfma_f32_16x16x32_bf16 v[34:37], v[56:59], v[14:17], v[34:37]
	ds_read2_b64 v[56:59], v64 offset0:160 offset1:164
	v_add3_u32 v41, v43, v41, s14
	v_and_b32_sdwa v43, v61, v179 dst_sel:DWORD dst_unused:UNUSED_PAD src0_sel:WORD_1 src1_sel:DWORD
	s_waitcnt lgkmcnt(2)
	v_mfma_f32_16x16x32_bf16 v[34:37], v[46:49], v[18:21], v[34:37]
	v_and_b32_sdwa v62, v60, v179 dst_sel:DWORD dst_unused:UNUSED_PAD src0_sel:WORD_1 src1_sel:DWORD
	v_add3_u32 v43, v61, v43, s14
	ds_read2_b64 v[46:49], v64 offset0:176 offset1:180
	s_waitcnt lgkmcnt(2)
	v_mfma_f32_16x16x32_bf16 v[34:37], v[52:55], v[22:25], v[34:37]
	v_add3_u32 v52, v60, v62, s14
	v_and_b32_e32 v43, 0xffff0000, v43
	v_and_b32_e32 v52, 0xffff0000, v52
	v_or_b32_sdwa v43, v43, v41 dst_sel:DWORD dst_unused:UNUSED_PAD src0_sel:DWORD src1_sel:WORD_1
	v_or_b32_sdwa v42, v52, v42 dst_sel:DWORD dst_unused:UNUSED_PAD src0_sel:DWORD src1_sel:WORD_1
	s_waitcnt vmcnt(2)
	v_lshlrev_b32_e32 v41, 16, v51
	v_lshlrev_b32_e32 v52, 16, v50
	global_store_dwordx2 v[38:39], v[42:43], off offset:32
	v_mul_f32_e32 v42, 0xbfb8aa3b, v52
	v_mul_f32_e32 v43, 0xbfb8aa3b, v41
	v_exp_f32_e32 v42, v42
	v_exp_f32_e32 v43, v43
	s_waitcnt lgkmcnt(1)
	v_mfma_f32_16x16x32_bf16 v[34:37], v[56:59], v[26:29], v[34:37]
	v_and_b32_e32 v56, 0xffff0000, v50
	v_and_b32_e32 v53, 0xffff0000, v51
	v_pk_add_f32 v[42:43], v[42:43], 1.0 op_sel_hi:[1,0]
	s_waitcnt lgkmcnt(0)
; __device__ __forceinline__ unsigned pk2(float lo, float hi) { return f2bf(lo) | (f2bf(hi) << 16); }
; __device__ __forceinline__ float bflo(unsigned u) { return __uint_as_float(u << 16); }
; __device__ __forceinline__ float bfhi(unsigned u) { return __uint_as_float(u & 0xffff0000u); }
; __device__ __forceinline__ float silu_f(float v) { return v / (1.f + __expf(-v)); }
; #define MFMA16(a, b, c) __builtin_amdgcn_mfma_f32_16x16x32_bf16(a, b, c, 0, 0, 0)
; __device__ __forceinline__ void na2_task(const Params& p_, int l, int task, unsigned char* lds) {
;     ...
;     for (int dt = 0; dt < 4; ++dt) { f32x4 o = {0.f, 0.f, 0.f, 0.f};
; #pragma unroll
;         for (int t = 0; t < 8; ++t) { const int k0 = 2 * t, k1 = 2 * t + 1, a0 = k0 / 2, c0 = k0 % 2, a1 = k1 / 2, c1 = k1 % 2;
;             const u32x2 vlo = *(const u32x2*)(VTh + (16 * dt + fr) * 520 + a0 * 64 + kst + 16 * c0 + 4 * fq), vhi = *(const u32x2*)(VTh + (16 * dt + fr) * 520 + a1 * 64 + kst + 16 * c1 + 4 * fq);
;             o = MFMA16(mk8(vlo.x, vlo.y, vhi.x, vhi.y), mk8(pp[k0][0], pp[k0][1], pp[k1][0], pp[k1][1]), o); }
;         const u32x2 gz = *(const u32x2*)(Z + qtok * DIN + 5 * DG + h * 64 + 16 * dt + 4 * fq); u32x2 ov;
;         ov.x = pk2(o[0] * inv * silu_f(bflo(gz.x)), o[1] * inv * silu_f(bfhi(gz.x))); ov.y = pk2(o[2] * inv * silu_f(bflo(gz.y)), o[3] * inv * silu_f(bfhi(gz.y)));
;         *(u32x2*)(CAT + qtok * DM + 512 + h * 64 + 16 * dt + 4 * fq) = ov; }
;     __syncthreads();
; __device__ __forceinline__ void ph_mixA(const Params& p, int l, unsigned char* lds) {
;     ...
;         for (int i = 0; i < nloc; ++i) { const int rq = (slot < 16) ? slot : 16 + i * 16 + (slot - 16);
;             na2_task(p, l, (xcd >> 2) * 256 + rq * 4 + (xcd & 3), lds); }
	v_mfma_f32_16x16x32_bf16 v[34:37], v[46:49], v[30:33], v[34:37]
	v_div_scale_f32 v47, s[12:13], v43, v43, v41
	v_rcp_f32_e32 v50, v47
	v_mul_f32_e32 v46, 0xbfb8aa3b, v56
	v_exp_f32_e32 v46, v46
	s_nop 3
	v_mov_b32_e32 v48, v34
	v_fma_f32 v34, -v47, v50, 1.0
	v_fmac_f32_e32 v50, v34, v50
	v_div_scale_f32 v34, vcc, v41, v43, v41
	v_mov_b32_e32 v49, v36
	v_mul_f32_e32 v36, v34, v50
	v_fma_f32 v51, -v47, v36, v34
	v_fmac_f32_e32 v36, v51, v50
	v_fma_f32 v34, -v47, v36, v34
	v_div_scale_f32 v47, s[12:13], v42, v42, v52
	v_rcp_f32_e32 v51, v47
	v_div_fmas_f32 v34, v34, v50, v36
	v_div_fixup_f32 v43, v34, v43, v41
	v_pk_mul_f32 v[48:49], v[40:41], v[48:49] op_sel_hi:[0,1]
	v_fma_f32 v34, -v47, v51, 1.0
	v_fmac_f32_e32 v51, v34, v51
	v_div_scale_f32 v34, vcc, v52, v42, v52
	v_mul_f32_e32 v36, v34, v51
	v_fma_f32 v41, -v47, v36, v34
	v_fmac_f32_e32 v36, v41, v51
	v_mul_f32_e32 v41, 0xbfb8aa3b, v53
	v_fma_f32 v34, -v47, v36, v34
	v_exp_f32_e32 v47, v41
	v_div_fmas_f32 v34, v34, v51, v36
	v_div_fixup_f32 v42, v34, v42, v52
	v_mov_b32_e32 v36, v35
	v_pk_add_f32 v[50:51], v[46:47], 1.0 op_sel_hi:[1,0]
	v_add_u32_e32 v0, 0xc000, v0
	v_div_scale_f32 v34, s[12:13], v51, v51, v53
	v_rcp_f32_e32 v41, v34
	v_div_scale_f32 v52, s[12:13], v50, v50, v56
	v_rcp_f32_e32 v58, v52
	v_fma_f32 v35, -v34, v41, 1.0
	v_pk_mul_f32 v[54:55], v[40:41], v[36:37] op_sel_hi:[0,1]
	v_fmac_f32_e32 v41, v35, v41
	v_div_scale_f32 v35, vcc, v53, v51, v53
	v_mul_f32_e32 v36, v35, v41
	v_fma_f32 v37, -v34, v36, v35
	v_fmac_f32_e32 v36, v37, v41
	v_fma_f32 v34, -v34, v36, v35
	v_div_fmas_f32 v34, v34, v41, v36
	v_div_fixup_f32 v57, v34, v51, v53
	ds_read2_b64 v[34:37], v0 offset0:96 offset1:100
	v_pk_mul_f32 v[42:43], v[48:49], v[42:43]
	ds_read2_b64 v[46:49], v0 offset0:112 offset1:116
	v_fma_f32 v41, -v52, v58, 1.0
	v_fmac_f32_e32 v58, v41, v58
	v_div_scale_f32 v41, vcc, v56, v50, v56
	v_mul_f32_e32 v51, v41, v58
	v_fma_f32 v53, -v52, v51, v41
	s_waitcnt lgkmcnt(1)
	v_mfma_f32_16x16x32_bf16 v[2:5], v[34:37], v[2:5], 0
	ds_read2_b64 v[34:37], v0 offset0:128 offset1:132
	v_fmac_f32_e32 v51, v53, v58
	v_fma_f32 v41, -v52, v51, v41
	v_div_fmas_f32 v41, v41, v58, v51
	v_div_fixup_f32 v56, v41, v50, v56
	ds_read2_b64 v[50:53], v0 offset0:144 offset1:148
	s_waitcnt lgkmcnt(2)
	v_mfma_f32_16x16x32_bf16 v[2:5], v[46:49], v[6:9], v[2:5]
	ds_read2_b64 v[6:9], v0 offset0:160 offset1:164
	v_pk_mul_f32 v[46:47], v[54:55], v[56:57]
	v_and_b32_sdwa v41, v43, v179 dst_sel:DWORD dst_unused:UNUSED_PAD src0_sel:WORD_1 src1_sel:DWORD
	s_waitcnt lgkmcnt(2)
	v_mfma_f32_16x16x32_bf16 v[2:5], v[34:37], v[10:13], v[2:5]
	v_and_b32_sdwa v10, v42, v179 dst_sel:DWORD dst_unused:UNUSED_PAD src0_sel:WORD_1 src1_sel:DWORD
	v_add3_u32 v34, v42, v10, s14
	ds_read2_b64 v[10:13], v0 offset0:176 offset1:180
	s_waitcnt lgkmcnt(2)
	v_mfma_f32_16x16x32_bf16 v[2:5], v[50:53], v[14:17], v[2:5]
	ds_read2_b64 v[14:17], v0 offset0:192 offset1:196
	v_and_b32_sdwa v36, v47, v179 dst_sel:DWORD dst_unused:UNUSED_PAD src0_sel:WORD_1 src1_sel:DWORD
	v_add3_u32 v35, v43, v41, s14
	s_waitcnt lgkmcnt(2)
	v_mfma_f32_16x16x32_bf16 v[2:5], v[6:9], v[18:21], v[2:5]
	ds_read2_b64 v[6:9], v0 offset0:208 offset1:212
	v_and_b32_sdwa v18, v46, v179 dst_sel:DWORD dst_unused:UNUSED_PAD src0_sel:WORD_1 src1_sel:DWORD
	v_add3_u32 v19, v47, v36, s14
	s_waitcnt lgkmcnt(2)
	v_mfma_f32_16x16x32_bf16 v[2:5], v[10:13], v[22:25], v[2:5]
	v_add3_u32 v0, v46, v18, s14
	v_and_b32_e32 v10, 0xffff0000, v19
	v_and_b32_e32 v0, 0xffff0000, v0
	s_waitcnt lgkmcnt(1)
	v_mfma_f32_16x16x32_bf16 v[2:5], v[14:17], v[26:29], v[2:5]
	v_or_b32_sdwa v11, v10, v35 dst_sel:DWORD dst_unused:UNUSED_PAD src0_sel:DWORD src1_sel:WORD_1
	v_or_b32_sdwa v10, v0, v34 dst_sel:DWORD dst_unused:UNUSED_PAD src0_sel:DWORD src1_sel:WORD_1
	s_waitcnt vmcnt(2)
	v_lshlrev_b32_e32 v0, 16, v45
	v_lshlrev_b32_e32 v12, 16, v44
	s_waitcnt lgkmcnt(0)
	v_mfma_f32_16x16x32_bf16 v[2:5], v[6:9], v[30:33], v[2:5]
	v_mul_f32_e32 v6, 0xbfb8aa3b, v12
	v_mul_f32_e32 v7, 0xbfb8aa3b, v0
	v_exp_f32_e32 v6, v6
	v_exp_f32_e32 v7, v7
	global_store_dwordx2 v[38:39], v[10:11], off offset:64
	s_nop 2
	v_mov_b32_e32 v10, v2
	v_mov_b32_e32 v11, v4
	v_pk_add_f32 v[6:7], v[6:7], 1.0 op_sel_hi:[1,0]
	v_and_b32_e32 v13, 0xffff0000, v45
	v_div_scale_f32 v9, s[12:13], v7, v7, v0
	v_rcp_f32_e32 v15, v9
	v_and_b32_e32 v14, 0xffff0000, v44
	v_mul_f32_e32 v8, 0xbfb8aa3b, v14
	v_exp_f32_e32 v8, v8
	v_fma_f32 v2, -v9, v15, 1.0
	v_fmac_f32_e32 v15, v2, v15
	v_div_scale_f32 v2, vcc, v0, v7, v0
	v_mul_f32_e32 v4, v2, v15
	v_fma_f32 v16, -v9, v4, v2
	v_fmac_f32_e32 v4, v16, v15
	v_fma_f32 v2, -v9, v4, v2
	v_div_scale_f32 v9, s[12:13], v6, v6, v12
	v_rcp_f32_e32 v16, v9
	v_div_fmas_f32 v2, v2, v15, v4
	v_div_fixup_f32 v7, v2, v7, v0
	v_pk_mul_f32 v[10:11], v[40:41], v[10:11] op_sel_hi:[0,1]
	v_fma_f32 v0, -v9, v16, 1.0
	v_fmac_f32_e32 v16, v0, v16
	v_div_scale_f32 v0, vcc, v12, v6, v12
	v_mul_f32_e32 v2, v0, v16
	v_fma_f32 v4, -v9, v2, v0
	v_fmac_f32_e32 v2, v4, v16
	v_mul_f32_e32 v4, 0xbfb8aa3b, v13
	v_fma_f32 v0, -v9, v2, v0
	v_exp_f32_e32 v9, v4
	v_div_fmas_f32 v0, v0, v16, v2
	v_div_fixup_f32 v6, v0, v6, v12
	v_mov_b32_e32 v4, v3
	v_pk_add_f32 v[8:9], v[8:9], 1.0 op_sel_hi:[1,0]
	v_pk_mul_f32 v[2:3], v[40:41], v[4:5] op_sel_hi:[0,1]
	v_div_scale_f32 v0, s[12:13], v9, v9, v13
	v_rcp_f32_e32 v12, v0
	v_pk_mul_f32 v[6:7], v[10:11], v[6:7]
	s_add_i32 s9, s3, 1
	s_cmp_lt_u32 s3, 3
	v_fma_f32 v4, -v0, v12, 1.0
	v_fmac_f32_e32 v12, v4, v12
	v_div_scale_f32 v4, vcc, v13, v9, v13
	v_mul_f32_e32 v5, v4, v12
	v_fma_f32 v10, -v0, v5, v4
	v_fmac_f32_e32 v5, v10, v12
	v_fma_f32 v0, -v0, v5, v4
	v_div_scale_f32 v4, s[12:13], v8, v8, v14
	v_rcp_f32_e32 v10, v4
	v_div_fmas_f32 v0, v0, v12, v5
	v_div_fixup_f32 v5, v0, v9, v13
	s_cselect_b64 s[12:13], -1, 0
	v_fma_f32 v0, -v4, v10, 1.0
	v_fmac_f32_e32 v10, v0, v10
	v_div_scale_f32 v0, vcc, v14, v8, v14
	v_mul_f32_e32 v9, v0, v10
	v_fma_f32 v11, -v4, v9, v0
	v_fmac_f32_e32 v9, v11, v10
	v_fma_f32 v0, -v4, v9, v0
	v_div_fmas_f32 v0, v0, v10, v9
	v_div_fixup_f32 v4, v0, v8, v14
	v_pk_mul_f32 v[2:3], v[2:3], v[4:5]
	v_and_b32_sdwa v4, v6, v179 dst_sel:DWORD dst_unused:UNUSED_PAD src0_sel:WORD_1 src1_sel:DWORD
	v_add3_u32 v4, v6, v4, s14
	v_and_b32_sdwa v5, v3, v179 dst_sel:DWORD dst_unused:UNUSED_PAD src0_sel:WORD_1 src1_sel:DWORD
	v_and_b32_sdwa v6, v2, v179 dst_sel:DWORD dst_unused:UNUSED_PAD src0_sel:WORD_1 src1_sel:DWORD
	v_and_b32_sdwa v0, v7, v179 dst_sel:DWORD dst_unused:UNUSED_PAD src0_sel:WORD_1 src1_sel:DWORD
	v_add3_u32 v3, v3, v5, s14
	v_add3_u32 v2, v2, v6, s14
	v_add3_u32 v0, v7, v0, s14
	v_and_b32_e32 v3, 0xffff0000, v3
	v_and_b32_e32 v2, 0xffff0000, v2
	s_and_b64 s[12:13], s[56:57], s[12:13]
	v_or_b32_sdwa v3, v3, v0 dst_sel:DWORD dst_unused:UNUSED_PAD src0_sel:DWORD src1_sel:WORD_1
	v_or_b32_sdwa v2, v2, v4 dst_sel:DWORD dst_unused:UNUSED_PAD src0_sel:DWORD src1_sel:WORD_1
	s_andn2_b64 vcc, exec, s[12:13]
	s_mov_b32 s3, s9
	global_store_dwordx2 v[38:39], v[2:3], off offset:96
	s_barrier
	s_cbranch_vccnz .LBB0_394

; __device__ __forceinline__ int obid() { int b = (int)blockIdx.x; asm volatile("" : "+s"(b)); return b; }
; __device__ __forceinline__ int otid() { int t; asm volatile("v_mov_b32 %0, %1" : "=v"(t) : "v"(threadIdx.x)); return t; }
; __device__ __forceinline__ unsigned pk2(float lo, float hi) { return f2bf(lo) | (f2bf(hi) << 16); }
; __device__ __forceinline__ float bf2f(bf16 b) { return __uint_as_float((unsigned)b << 16); }
; __device__ __forceinline__ float bflo(unsigned u) { return __uint_as_float(u << 16); }
; __device__ __forceinline__ float bfhi(unsigned u) { return __uint_as_float(u & 0xffff0000u); }
; __device__ __forceinline__ void ph_fold(const Params& p_) {
;     ...
;     for (int e = obid() * NTHR + otid(); e < NB * DG * 2 * 256; e += gridDim.x * NTHR) {
;         const int row = e >> 8, s0 = (e & 255) * 8, pq = row & 1;
;         const bf16* src = PQ + (size_t)row * 4096;
;         const u32x4 own = *(const u32x4*)(src + s0), low = *(const u32x4*)(src + 4096 - s0 - 8);
;         const float top = (s0 == 0) ? 0.f : bf2f(src[4096 - s0]);
;         const float sg = pq ? -1.f : 1.f;
;         float o[8];
;         o[0] = bflo(own.x) + sg * top;            o[1] = bfhi(own.x) + sg * bfhi(low.w);
;         o[2] = bflo(own.y) + sg * bflo(low.w);    o[3] = bfhi(own.y) + sg * bfhi(low.z);
;         o[4] = bflo(own.z) + sg * bflo(low.z);    o[5] = bfhi(own.z) + sg * bfhi(low.y);
;         o[6] = bflo(own.w) + sg * bflo(low.y);    o[7] = bfhi(own.w) + sg * bfhi(low.x);
;         if (s0 == 0 && pq) o[0] = 0.f;
;         u32x4 w; w.x = pk2(o[0], o[1]); w.y = pk2(o[2], o[3]); w.z = pk2(o[4], o[5]); w.w = pk2(o[6], o[7]);
;         *(u32x4*)(PQF + (size_t)row * 2048 + s0) = w;
;     }
.LBB0_451:
	s_mov_b64 s[36:37], s[0:1]
	s_mov_b32 s3, s70
	s_mov_b32 s54, 0x7ffff
	s_movk_i32 s55, 0x80
	s_cmp_lt_u32 s3, s55
	s_cselect_b32 s54, 0x5ffff, s54
	s_mov_b32 s55, 0x10000
	v_mov_b32 v0, v147
	s_mov_b32 s6, 0x80000
	v_lshl_add_u32 v14, s3, 9, v0
	v_cmp_gt_i32_e32 vcc, s6, v14
	s_and_saveexec_b64 s[12:13], vcc
	s_xor_b64 s[38:39], exec, s[12:13]
	s_movk_i32 s68, 0x800
	v_readlane_b32 s24, v255, 36
	s_cbranch_execz .LBB0_457
	s_load_dwordx2 s[12:13], s[36:37], 0x90
	v_lshlrev_b32_e32 v0, 3, v0
	v_lshl_add_u32 v15, s3, 12, v0
	s_mov_b64 s[44:45], 0
	s_waitcnt lgkmcnt(0)
	s_add_u32 s40, s12, 0x11520000
	s_addc_u32 s41, s13, 0
	s_add_u32 s42, s12, 0x6400000
	s_addc_u32 s43, s13, 0
	s_branch .LBB0_454
.LBB0_453:
	s_or_b64 exec, exec, s[46:47]
	v_and_b32_e32 v12, 0x100, v14
	v_cmp_ne_u32_e64 s[36:37], 0, v12
	s_waitcnt vmcnt(0)
	v_lshlrev_b32_e32 v13, 16, v6
	s_and_b64 s[12:13], s[36:37], vcc
	v_cndmask_b32_e64 v12, 1.0, -1.0, s[36:37]
	v_fmac_f32_e32 v13, v12, v17
	v_and_b32_e32 v6, 0xffff0000, v6
	v_and_b32_e32 v16, 0xffff0000, v5
	v_cndmask_b32_e64 v13, v13, 0, s[12:13]
	v_fmac_f32_e32 v6, v12, v16
	v_bfe_u32 v16, v13, 16, 1
	v_add3_u32 v13, v13, v16, s14
	v_lshrrev_b32_e32 v13, 16, v13
	v_bfe_u32 v16, v6, 16, 1
	v_lshlrev_b32_e32 v19, 16, v5
	v_lshlrev_b32_e32 v18, 16, v4
	v_add3_u32 v6, v6, v16, s14
	v_lshlrev_b32_e32 v17, 16, v8
	v_lshlrev_b32_e32 v16, 16, v7
	v_pk_mul_f32 v[18:19], v[12:13], v[18:19] op_sel_hi:[0,1]
	v_and_b32_e32 v5, 0xffff0000, v4
	v_and_b32_e32 v4, 0xffff0000, v3
	v_pk_add_f32 v[16:17], v[18:19], v[16:17] op_sel:[1,0] op_sel_hi:[0,1]
	v_and_b32_e32 v19, 0xffff0000, v8
	v_and_b32_e32 v18, 0xffff0000, v7
	v_pk_mul_f32 v[4:5], v[12:13], v[4:5] op_sel_hi:[0,1]
	v_pk_add_f32 v[4:5], v[4:5], v[18:19] op_sel:[1,0] op_sel_hi:[0,1]
	v_and_b32_sdwa v8, v16, v179 dst_sel:DWORD dst_unused:UNUSED_PAD src0_sel:WORD_1 src1_sel:DWORD
	v_and_or_b32 v6, v6, s15, v13
	v_add3_u32 v13, v16, v8, s14
	v_and_b32_sdwa v8, v5, v179 dst_sel:DWORD dst_unused:UNUSED_PAD src0_sel:WORD_1 src1_sel:DWORD
	v_and_b32_sdwa v16, v4, v179 dst_sel:DWORD dst_unused:UNUSED_PAD src0_sel:WORD_1 src1_sel:DWORD
	v_and_b32_sdwa v7, v17, v179 dst_sel:DWORD dst_unused:UNUSED_PAD src0_sel:WORD_1 src1_sel:DWORD
	v_add3_u32 v5, v5, v8, s14
	v_add3_u32 v4, v4, v16, s14
	v_add3_u32 v7, v17, v7, s14
	v_and_b32_e32 v5, 0xffff0000, v5
	v_and_b32_e32 v4, 0xffff0000, v4
	v_or_b32_sdwa v8, v5, v7 dst_sel:DWORD dst_unused:UNUSED_PAD src0_sel:DWORD src1_sel:WORD_1
	v_or_b32_sdwa v7, v4, v13 dst_sel:DWORD dst_unused:UNUSED_PAD src0_sel:DWORD src1_sel:WORD_1
	v_and_b32_e32 v4, 0xffff0000, v9
	v_lshlrev_b32_e32 v5, 16, v9
	v_and_b32_e32 v2, 0xffff0000, v2
	v_lshlrev_b32_e32 v3, 16, v3
	v_pk_fma_f32 v[2:3], v[12:13], v[2:3], v[4:5] op_sel_hi:[0,1,1]
	v_and_b32_sdwa v4, v3, v179 dst_sel:DWORD dst_unused:UNUSED_PAD src0_sel:WORD_1 src1_sel:DWORD
	v_and_b32_sdwa v5, v2, v179 dst_sel:DWORD dst_unused:UNUSED_PAD src0_sel:WORD_1 src1_sel:DWORD
	v_add3_u32 v3, v3, v4, s14
	v_add3_u32 v2, v2, v5, s14
	v_lshrrev_b32_e32 v3, 16, v3
	v_and_or_b32 v9, v2, s15, v3
	v_lshlrev_b64 v[2:3], 12, v[10:11]
	v_cmp_gt_i32_e32 vcc, 0x50000, v14
	s_nop 1
	v_cndmask_b32_e64 v20, 0, 1, vcc
	v_lshlrev_b32_e32 v20, 16, v20
	v_add3_u32 v14, v14, v20, s55
	s_mov_b32 s3, s54
	v_lshl_add_u64 v[2:3], s[42:43], 0, v[2:3]
	v_cmp_lt_i32_e32 vcc, s3, v14
	v_lshl_add_u64 v[2:3], v[2:3], 0, v[0:1]
	s_or_b64 s[44:45], vcc, s[44:45]
	v_add_u32_e32 v15, s24, v15
	global_store_dwordx4 v[2:3], v[6:9], off
	s_andn2_b64 exec, exec, s[44:45]
	s_cbranch_execz .LBB0_456
